# v6 plus: MFMAs of each 16-block reordered so the two k-steps of an accumulator are back to back (SrcC forwarding), dependency-checked, bit-identical
# speedup vs baseline: 1.0106x; 1.0106x over previous
.LBB0_230:
	s_add_u32 s28, s0, 0xfff00080
	s_addc_u32 s29, s1, -1
	s_add_i32 s51, 0, 0x10000
	s_cmp_eq_u32 s50, 60
	s_cselect_b32 s31, s34, s29
	s_cselect_b32 s30, s35, s28
	v_add_u32_e32 v0, s51, v179
	s_cselect_b32 s29, s27, s43
	s_cselect_b32 s28, s40, s41
	s_add_i32 s77, 0, 0x14000
	ds_read_b128 v[130:133], v0
	ds_read_b128 v[134:137], v0 offset:1024
	ds_read_b128 v[138:141], v0 offset:2048
	ds_read_b128 v[142:145], v0 offset:3072
	v_add_u32_e32 v0, s77, v179
	ds_read_b128 v[146:149], v0
	ds_read_b128 v[150:153], v0 offset:1024
	ds_read_b128 v[154:157], v0 offset:2048
	ds_read_b128 v[158:161], v0 offset:3072
	v_lshl_add_u64 v[194:195], s[0:1], 0, v[170:171]
	s_add_i32 m0, s14, 0xc000
	ds_read_b128 v[174:177], v192
	ds_read_b128 v[180:183], v192 offset:1024
	ds_read_b128 v[184:187], v192 offset:2048
	ds_read_b128 v[188:191], v192 offset:3072
	ds_read_b128 v[200:203], v192 offset:4096
	ds_read_b128 v[204:207], v192 offset:5120
	ds_read_b128 v[208:211], v192 offset:6144
	ds_read_b128 v[212:215], v192 offset:7168
	global_load_lds_dwordx4 v[194:195], off
	v_lshl_add_u64 v[194:195], s[0:1], 0, v[172:173]
	s_add_i32 m0, s14, 0xe000
	s_nop 0
	global_load_lds_dwordx4 v[194:195], off
	s_waitcnt vmcnt(8)
	s_waitcnt lgkmcnt(0)
	s_barrier
	s_waitcnt lgkmcnt(0)
	v_mfma_f32_16x16x32_bf16 v[126:129], v[130:133], v[174:177], v[126:129]
	v_mfma_f32_16x16x32_bf16 v[126:129], v[134:137], v[180:183], v[126:129]
	v_mfma_f32_16x16x32_bf16 v[122:125], v[138:141], v[174:177], v[122:125]
	v_mfma_f32_16x16x32_bf16 v[122:125], v[142:145], v[180:183], v[122:125]
	v_mfma_f32_16x16x32_bf16 v[110:113], v[130:133], v[184:187], v[110:113]
	v_mfma_f32_16x16x32_bf16 v[110:113], v[134:137], v[188:191], v[110:113]
	v_mfma_f32_16x16x32_bf16 v[106:109], v[138:141], v[184:187], v[106:109]
	v_mfma_f32_16x16x32_bf16 v[106:109], v[142:145], v[188:191], v[106:109]
	v_mfma_f32_16x16x32_bf16 v[94:97], v[130:133], v[200:203], v[94:97]
	v_mfma_f32_16x16x32_bf16 v[94:97], v[134:137], v[204:207], v[94:97]
	v_mfma_f32_16x16x32_bf16 v[90:93], v[138:141], v[200:203], v[90:93]
	v_mfma_f32_16x16x32_bf16 v[90:93], v[142:145], v[204:207], v[90:93]
	v_mfma_f32_16x16x32_bf16 v[78:81], v[130:133], v[208:211], v[78:81]
	v_mfma_f32_16x16x32_bf16 v[78:81], v[134:137], v[212:215], v[78:81]
	v_mfma_f32_16x16x32_bf16 v[74:77], v[138:141], v[208:211], v[74:77]
	v_mfma_f32_16x16x32_bf16 v[74:77], v[142:145], v[212:215], v[74:77]
	v_mfma_f32_16x16x32_bf16 v[118:121], v[146:149], v[174:177], v[118:121]
	v_mfma_f32_16x16x32_bf16 v[118:121], v[150:153], v[180:183], v[118:121]
	v_mfma_f32_16x16x32_bf16 v[114:117], v[154:157], v[174:177], v[114:117]
	v_mfma_f32_16x16x32_bf16 v[114:117], v[158:161], v[180:183], v[114:117]
	v_mfma_f32_16x16x32_bf16 v[102:105], v[146:149], v[184:187], v[102:105]
	v_mfma_f32_16x16x32_bf16 v[102:105], v[150:153], v[188:191], v[102:105]
	v_mfma_f32_16x16x32_bf16 v[98:101], v[154:157], v[184:187], v[98:101]
	v_mfma_f32_16x16x32_bf16 v[98:101], v[158:161], v[188:191], v[98:101]
	v_mfma_f32_16x16x32_bf16 v[86:89], v[146:149], v[200:203], v[86:89]
	v_mfma_f32_16x16x32_bf16 v[86:89], v[150:153], v[204:207], v[86:89]
	v_mfma_f32_16x16x32_bf16 v[82:85], v[154:157], v[200:203], v[82:85]
	v_mfma_f32_16x16x32_bf16 v[82:85], v[158:161], v[204:207], v[82:85]
	v_mfma_f32_16x16x32_bf16 v[70:73], v[146:149], v[208:211], v[70:73]
	v_mfma_f32_16x16x32_bf16 v[70:73], v[150:153], v[212:215], v[70:73]
	v_mfma_f32_16x16x32_bf16 v[66:69], v[154:157], v[208:211], v[66:69]
	v_mfma_f32_16x16x32_bf16 v[66:69], v[158:161], v[212:215], v[66:69]
	s_barrier
	s_add_i32 s51, s51, s9
	v_lshl_add_u64 v[194:195], s[28:29], 0, v[166:167]
	s_mov_b32 m0, s51
	ds_read_b128 v[174:177], v192 offset:16384
	ds_read_b128 v[180:183], v192 offset:17408
	ds_read_b128 v[184:187], v192 offset:18432
	ds_read_b128 v[188:191], v192 offset:19456
	ds_read_b128 v[200:203], v192 offset:20480
	ds_read_b128 v[204:207], v192 offset:21504
	ds_read_b128 v[208:211], v192 offset:22528
	ds_read_b128 v[212:215], v192 offset:23552
	global_load_lds_dwordx4 v[194:195], off
	s_add_i32 m0, s51, 0x2000
	s_add_u32 s80, s28, 0x100000
	v_lshl_add_u64 v[216:217], s[28:29], 0, v[162:163]
	s_addc_u32 s81, s29, 0
	s_add_i32 s51, s77, s9
	global_load_lds_dwordx4 v[216:217], off
	v_lshl_add_u64 v[218:219], s[80:81], 0, v[166:167]
	s_mov_b32 m0, s51
	v_lshl_add_u64 v[220:221], s[30:31], 0, v[164:165]
	global_load_lds_dwordx4 v[218:219], off
	v_lshl_add_u64 v[218:219], s[80:81], 0, v[162:163]
	s_add_i32 m0, s51, 0x2000
	s_nop 0
	global_load_lds_dwordx4 v[218:219], off
	v_lshl_add_u64 v[218:219], s[30:31], 0, v[168:169]
	s_mov_b32 m0, s14
	s_nop 0
	global_load_lds_dwordx4 v[218:219], off
	s_mov_b32 m0, s15
	s_nop 0
	global_load_lds_dwordx4 v[220:221], off
	s_waitcnt vmcnt(8)
	s_waitcnt lgkmcnt(0)
	s_barrier
	s_waitcnt lgkmcnt(0)
	v_mfma_f32_16x16x32_bf16 v[62:65], v[130:133], v[174:177], v[62:65]
	v_mfma_f32_16x16x32_bf16 v[62:65], v[134:137], v[180:183], v[62:65]
	v_mfma_f32_16x16x32_bf16 v[58:61], v[138:141], v[174:177], v[58:61]
	v_mfma_f32_16x16x32_bf16 v[58:61], v[142:145], v[180:183], v[58:61]
	v_mfma_f32_16x16x32_bf16 v[46:49], v[130:133], v[184:187], v[46:49]
	v_mfma_f32_16x16x32_bf16 v[46:49], v[134:137], v[188:191], v[46:49]
	v_mfma_f32_16x16x32_bf16 v[42:45], v[138:141], v[184:187], v[42:45]
	v_mfma_f32_16x16x32_bf16 v[42:45], v[142:145], v[188:191], v[42:45]
	v_mfma_f32_16x16x32_bf16 v[30:33], v[130:133], v[200:203], v[30:33]
	v_mfma_f32_16x16x32_bf16 v[30:33], v[134:137], v[204:207], v[30:33]
	v_mfma_f32_16x16x32_bf16 v[26:29], v[138:141], v[200:203], v[26:29]
	v_mfma_f32_16x16x32_bf16 v[26:29], v[142:145], v[204:207], v[26:29]
	v_mfma_f32_16x16x32_bf16 v[14:17], v[130:133], v[208:211], v[14:17]
	v_mfma_f32_16x16x32_bf16 v[14:17], v[134:137], v[212:215], v[14:17]
	v_mfma_f32_16x16x32_bf16 v[10:13], v[138:141], v[208:211], v[10:13]
	v_mfma_f32_16x16x32_bf16 v[10:13], v[142:145], v[212:215], v[10:13]
	v_mfma_f32_16x16x32_bf16 v[54:57], v[146:149], v[174:177], v[54:57]
	v_mfma_f32_16x16x32_bf16 v[54:57], v[150:153], v[180:183], v[54:57]
	v_mfma_f32_16x16x32_bf16 v[50:53], v[154:157], v[174:177], v[50:53]
	v_mfma_f32_16x16x32_bf16 v[50:53], v[158:161], v[180:183], v[50:53]
	v_mfma_f32_16x16x32_bf16 v[38:41], v[146:149], v[184:187], v[38:41]
	v_mfma_f32_16x16x32_bf16 v[38:41], v[150:153], v[188:191], v[38:41]
	v_mfma_f32_16x16x32_bf16 v[34:37], v[154:157], v[184:187], v[34:37]
	v_mfma_f32_16x16x32_bf16 v[34:37], v[158:161], v[188:191], v[34:37]
	v_mfma_f32_16x16x32_bf16 v[22:25], v[146:149], v[200:203], v[22:25]
	v_mfma_f32_16x16x32_bf16 v[22:25], v[150:153], v[204:207], v[22:25]
	v_mfma_f32_16x16x32_bf16 v[18:21], v[154:157], v[200:203], v[18:21]
	v_mfma_f32_16x16x32_bf16 v[18:21], v[158:161], v[204:207], v[18:21]
	v_mfma_f32_16x16x32_bf16 v[6:9], v[146:149], v[208:211], v[6:9]
	v_mfma_f32_16x16x32_bf16 v[6:9], v[150:153], v[212:215], v[6:9]
	v_mfma_f32_16x16x32_bf16 v[2:5], v[154:157], v[208:211], v[2:5]
	v_mfma_f32_16x16x32_bf16 v[2:5], v[158:161], v[212:215], v[2:5]
	s_barrier
	s_add_i32 s51, 0, 0x18000
	v_add_u32_e32 v0, s51, v179
	s_add_i32 s77, 0, 0x1c000
	ds_read_b128 v[130:133], v0
	ds_read_b128 v[134:137], v0 offset:1024
	ds_read_b128 v[138:141], v0 offset:2048
	ds_read_b128 v[142:145], v0 offset:3072
	v_add_u32_e32 v0, s77, v179
	ds_read_b128 v[146:149], v0
	ds_read_b128 v[150:153], v0 offset:1024
	ds_read_b128 v[154:157], v0 offset:2048
	ds_read_b128 v[158:161], v0 offset:3072
	s_add_u32 s30, s30, 0x100000
	s_addc_u32 s31, s31, 0
	s_mov_b32 m0, s52
	v_lshl_add_u64 v[222:223], s[30:31], 0, v[168:169]
	ds_read_b128 v[174:177], v192 offset:32768
	ds_read_b128 v[180:183], v192 offset:33792
	ds_read_b128 v[184:187], v192 offset:34816
	ds_read_b128 v[188:191], v192 offset:35840
	ds_read_b128 v[200:203], v192 offset:36864
	ds_read_b128 v[204:207], v192 offset:37888
	ds_read_b128 v[208:211], v192 offset:38912
	ds_read_b128 v[212:215], v192 offset:39936
	global_load_lds_dwordx4 v[222:223], off
	v_lshl_add_u64 v[222:223], s[30:31], 0, v[164:165]
	s_mov_b32 m0, s53
	s_nop 0
	global_load_lds_dwordx4 v[222:223], off
	s_waitcnt vmcnt(8)
	s_waitcnt lgkmcnt(0)
	s_barrier
	s_waitcnt lgkmcnt(0)
	v_mfma_f32_16x16x32_bf16 v[126:129], v[130:133], v[174:177], v[126:129]
	v_mfma_f32_16x16x32_bf16 v[126:129], v[134:137], v[180:183], v[126:129]
	v_mfma_f32_16x16x32_bf16 v[122:125], v[138:141], v[174:177], v[122:125]
	v_mfma_f32_16x16x32_bf16 v[122:125], v[142:145], v[180:183], v[122:125]
	v_mfma_f32_16x16x32_bf16 v[110:113], v[130:133], v[184:187], v[110:113]
	v_mfma_f32_16x16x32_bf16 v[110:113], v[134:137], v[188:191], v[110:113]
	v_mfma_f32_16x16x32_bf16 v[106:109], v[138:141], v[184:187], v[106:109]
	v_mfma_f32_16x16x32_bf16 v[106:109], v[142:145], v[188:191], v[106:109]
	v_mfma_f32_16x16x32_bf16 v[94:97], v[130:133], v[200:203], v[94:97]
	v_mfma_f32_16x16x32_bf16 v[94:97], v[134:137], v[204:207], v[94:97]
	v_mfma_f32_16x16x32_bf16 v[90:93], v[138:141], v[200:203], v[90:93]
	v_mfma_f32_16x16x32_bf16 v[90:93], v[142:145], v[204:207], v[90:93]
	v_mfma_f32_16x16x32_bf16 v[78:81], v[130:133], v[208:211], v[78:81]
	v_mfma_f32_16x16x32_bf16 v[78:81], v[134:137], v[212:215], v[78:81]
	v_mfma_f32_16x16x32_bf16 v[74:77], v[138:141], v[208:211], v[74:77]
	v_mfma_f32_16x16x32_bf16 v[74:77], v[142:145], v[212:215], v[74:77]
	v_mfma_f32_16x16x32_bf16 v[118:121], v[146:149], v[174:177], v[118:121]
	v_mfma_f32_16x16x32_bf16 v[118:121], v[150:153], v[180:183], v[118:121]
	v_mfma_f32_16x16x32_bf16 v[114:117], v[154:157], v[174:177], v[114:117]
	v_mfma_f32_16x16x32_bf16 v[114:117], v[158:161], v[180:183], v[114:117]
	v_mfma_f32_16x16x32_bf16 v[102:105], v[146:149], v[184:187], v[102:105]
	v_mfma_f32_16x16x32_bf16 v[102:105], v[150:153], v[188:191], v[102:105]
	v_mfma_f32_16x16x32_bf16 v[98:101], v[154:157], v[184:187], v[98:101]
	v_mfma_f32_16x16x32_bf16 v[98:101], v[158:161], v[188:191], v[98:101]
	v_mfma_f32_16x16x32_bf16 v[86:89], v[146:149], v[200:203], v[86:89]
	v_mfma_f32_16x16x32_bf16 v[86:89], v[150:153], v[204:207], v[86:89]
	v_mfma_f32_16x16x32_bf16 v[82:85], v[154:157], v[200:203], v[82:85]
	v_mfma_f32_16x16x32_bf16 v[82:85], v[158:161], v[204:207], v[82:85]
	v_mfma_f32_16x16x32_bf16 v[70:73], v[146:149], v[208:211], v[70:73]
	v_mfma_f32_16x16x32_bf16 v[70:73], v[150:153], v[212:215], v[70:73]
	v_mfma_f32_16x16x32_bf16 v[66:69], v[154:157], v[208:211], v[66:69]
	v_mfma_f32_16x16x32_bf16 v[66:69], v[158:161], v[212:215], v[66:69]
	s_barrier
	s_add_i32 s30, s51, s9
	v_lshl_add_u64 v[194:195], v[194:195], 0, s[12:13]
	s_mov_b32 m0, s30
	ds_read_b128 v[174:177], v192 offset:49152
	ds_read_b128 v[180:183], v192 offset:50176
	ds_read_b128 v[184:187], v192 offset:51200
	ds_read_b128 v[188:191], v192 offset:52224
	ds_read_b128 v[200:203], v192 offset:53248
	ds_read_b128 v[204:207], v192 offset:54272
	ds_read_b128 v[208:211], v192 offset:55296
	ds_read_b128 v[212:215], v192 offset:56320
	global_load_lds_dwordx4 v[194:195], off
	s_add_i32 m0, s30, 0x2000
	s_add_u32 s28, s28, 0x100080
	v_lshl_add_u64 v[194:195], v[216:217], 0, s[12:13]
	s_addc_u32 s29, s29, 0
	s_add_i32 s30, s77, s9
	global_load_lds_dwordx4 v[194:195], off
	v_lshl_add_u64 v[194:195], s[28:29], 0, v[166:167]
	s_mov_b32 m0, s30
	s_nop 0
	global_load_lds_dwordx4 v[194:195], off
	v_lshl_add_u64 v[194:195], s[28:29], 0, v[162:163]
	s_add_i32 m0, s30, 0x2000
	s_nop 0
	global_load_lds_dwordx4 v[194:195], off
	v_lshl_add_u64 v[194:195], v[218:219], 0, s[12:13]
	s_mov_b32 m0, s54
	s_nop 0
	global_load_lds_dwordx4 v[194:195], off
	v_lshl_add_u64 v[194:195], v[220:221], 0, s[12:13]
	s_mov_b32 m0, s55
	s_nop 0
	global_load_lds_dwordx4 v[194:195], off
	s_waitcnt vmcnt(8)
	s_waitcnt lgkmcnt(0)
	s_barrier
	s_waitcnt lgkmcnt(0)
	v_mfma_f32_16x16x32_bf16 v[62:65], v[130:133], v[174:177], v[62:65]
	v_mfma_f32_16x16x32_bf16 v[62:65], v[134:137], v[180:183], v[62:65]
	v_mfma_f32_16x16x32_bf16 v[58:61], v[138:141], v[174:177], v[58:61]
	v_mfma_f32_16x16x32_bf16 v[58:61], v[142:145], v[180:183], v[58:61]
	v_mfma_f32_16x16x32_bf16 v[46:49], v[130:133], v[184:187], v[46:49]
	v_mfma_f32_16x16x32_bf16 v[46:49], v[134:137], v[188:191], v[46:49]
	v_mfma_f32_16x16x32_bf16 v[42:45], v[138:141], v[184:187], v[42:45]
	v_mfma_f32_16x16x32_bf16 v[42:45], v[142:145], v[188:191], v[42:45]
	v_mfma_f32_16x16x32_bf16 v[30:33], v[130:133], v[200:203], v[30:33]
	v_mfma_f32_16x16x32_bf16 v[30:33], v[134:137], v[204:207], v[30:33]
	v_mfma_f32_16x16x32_bf16 v[26:29], v[138:141], v[200:203], v[26:29]
	v_mfma_f32_16x16x32_bf16 v[26:29], v[142:145], v[204:207], v[26:29]
	v_mfma_f32_16x16x32_bf16 v[14:17], v[130:133], v[208:211], v[14:17]
	v_mfma_f32_16x16x32_bf16 v[14:17], v[134:137], v[212:215], v[14:17]
	v_mfma_f32_16x16x32_bf16 v[10:13], v[138:141], v[208:211], v[10:13]
	v_mfma_f32_16x16x32_bf16 v[10:13], v[142:145], v[212:215], v[10:13]
	v_mfma_f32_16x16x32_bf16 v[54:57], v[146:149], v[174:177], v[54:57]
	v_mfma_f32_16x16x32_bf16 v[54:57], v[150:153], v[180:183], v[54:57]
	v_mfma_f32_16x16x32_bf16 v[50:53], v[154:157], v[174:177], v[50:53]
	v_mfma_f32_16x16x32_bf16 v[50:53], v[158:161], v[180:183], v[50:53]
	v_mfma_f32_16x16x32_bf16 v[38:41], v[146:149], v[184:187], v[38:41]
	v_mfma_f32_16x16x32_bf16 v[38:41], v[150:153], v[188:191], v[38:41]
	v_mfma_f32_16x16x32_bf16 v[34:37], v[154:157], v[184:187], v[34:37]
	v_mfma_f32_16x16x32_bf16 v[34:37], v[158:161], v[188:191], v[34:37]
	v_mfma_f32_16x16x32_bf16 v[22:25], v[146:149], v[200:203], v[22:25]
	v_mfma_f32_16x16x32_bf16 v[22:25], v[150:153], v[204:207], v[22:25]
	v_mfma_f32_16x16x32_bf16 v[18:21], v[154:157], v[200:203], v[18:21]
	v_mfma_f32_16x16x32_bf16 v[18:21], v[158:161], v[204:207], v[18:21]
	v_mfma_f32_16x16x32_bf16 v[6:9], v[146:149], v[208:211], v[6:9]
	v_mfma_f32_16x16x32_bf16 v[6:9], v[150:153], v[212:215], v[6:9]
	v_mfma_f32_16x16x32_bf16 v[2:5], v[154:157], v[208:211], v[2:5]
	v_mfma_f32_16x16x32_bf16 v[2:5], v[158:161], v[212:215], v[2:5]
	s_barrier
	s_add_i32 s50, s50, 2
	s_add_u32 s0, s0, 0x100
	s_addc_u32 s1, s1, 0
	s_add_u32 s41, s41, 0x100
	s_addc_u32 s43, s43, 0
	s_cmp_gt_u32 s50, 61
	s_cbranch_scc0 .LBB0_230
	s_and_b64 vcc, exec, s[22:23]
	s_cbranch_vccz .LBB0_233
	s_barrier

.LBB0_300:
	s_add_u32 s100, s0, 0xfff80000
	s_addc_u32 s101, s1, -1
	s_add_u32 s28, s0, 0xfff80080
	s_addc_u32 s29, s1, -1
	s_add_i32 s42, 0, 0x10000
	s_cmp_eq_u32 s41, 28
	s_cselect_b32 s31, s18, s29
	s_cselect_b32 s30, s19, s28
	v_add_u32_e32 v0, s42, v199
	s_cselect_b32 s29, s27, s40
	s_cselect_b32 s28, s34, s35
	s_add_i32 s49, 0, 0x14000
	ds_read_b128 v[2:5], v0
	ds_read_b128 v[6:9], v0 offset:1024
	ds_read_b128 v[10:13], v0 offset:2048
	ds_read_b128 v[14:17], v0 offset:3072
	v_add_u32_e32 v0, s49, v199
	ds_read_b128 v[146:149], v0
	ds_read_b128 v[150:153], v0 offset:1024
	ds_read_b128 v[154:157], v0 offset:2048
	ds_read_b128 v[158:161], v0 offset:3072
	v_lshl_add_u64 v[194:195], s[100:101], 0, v[162:163]
	s_mov_b32 m0, s15
	ds_read_b128 v[174:177], v250
	ds_read_b128 v[178:181], v250 offset:1024
	ds_read_b128 v[182:185], v250 offset:2048
	ds_read_b128 v[186:189], v250 offset:3072
	ds_read_b128 v[190:193], v250 offset:4096
	ds_read_b128 v[200:203], v250 offset:5120
	ds_read_b128 v[204:207], v250 offset:6144
	ds_read_b128 v[208:211], v250 offset:7168
	global_load_lds_dwordx4 v[194:195], off
	v_lshl_add_u64 v[194:195], s[100:101], 0, v[166:167]
	s_mov_b32 m0, s88
	s_nop 0
	global_load_lds_dwordx4 v[194:195], off
	v_lshl_add_u64 v[194:195], s[0:1], 0, v[170:171]
	s_add_i32 m0, s21, 0xc000
	s_nop 0
	global_load_lds_dwordx4 v[194:195], off
	v_lshl_add_u64 v[194:195], s[0:1], 0, v[172:173]
	s_add_i32 m0, s21, 0xe000
	s_nop 0
	global_load_lds_dwordx4 v[194:195], off
	s_waitcnt vmcnt(8)
	s_waitcnt lgkmcnt(0)
	s_barrier
	s_waitcnt lgkmcnt(0)
	v_mfma_i32_16x16x64_i8 v[142:145], v[2:5], v[174:177], v[142:145]
	v_mfma_i32_16x16x64_i8 v[142:145], v[6:9], v[178:181], v[142:145]
	v_mfma_i32_16x16x64_i8 v[138:141], v[10:13], v[174:177], v[138:141]
	v_mfma_i32_16x16x64_i8 v[138:141], v[14:17], v[178:181], v[138:141]
	v_mfma_i32_16x16x64_i8 v[134:137], v[2:5], v[182:185], v[134:137]
	v_mfma_i32_16x16x64_i8 v[134:137], v[6:9], v[186:189], v[134:137]
	v_mfma_i32_16x16x64_i8 v[130:133], v[10:13], v[182:185], v[130:133]
	v_mfma_i32_16x16x64_i8 v[130:133], v[14:17], v[186:189], v[130:133]
	v_mfma_i32_16x16x64_i8 v[122:125], v[2:5], v[190:193], v[122:125]
	v_mfma_i32_16x16x64_i8 v[122:125], v[6:9], v[200:203], v[122:125]
	v_mfma_i32_16x16x64_i8 v[114:117], v[10:13], v[190:193], v[114:117]
	v_mfma_i32_16x16x64_i8 v[114:117], v[14:17], v[200:203], v[114:117]
	v_mfma_i32_16x16x64_i8 v[106:109], v[2:5], v[204:207], v[106:109]
	v_mfma_i32_16x16x64_i8 v[106:109], v[6:9], v[208:211], v[106:109]
	v_mfma_i32_16x16x64_i8 v[98:101], v[10:13], v[204:207], v[98:101]
	v_mfma_i32_16x16x64_i8 v[98:101], v[14:17], v[208:211], v[98:101]
	v_mfma_i32_16x16x64_i8 v[126:129], v[146:149], v[174:177], v[126:129]
	v_mfma_i32_16x16x64_i8 v[126:129], v[150:153], v[178:181], v[126:129]
	v_mfma_i32_16x16x64_i8 v[118:121], v[154:157], v[174:177], v[118:121]
	v_mfma_i32_16x16x64_i8 v[118:121], v[158:161], v[178:181], v[118:121]
	v_mfma_i32_16x16x64_i8 v[110:113], v[146:149], v[182:185], v[110:113]
	v_mfma_i32_16x16x64_i8 v[110:113], v[150:153], v[186:189], v[110:113]
	v_mfma_i32_16x16x64_i8 v[102:105], v[154:157], v[182:185], v[102:105]
	v_mfma_i32_16x16x64_i8 v[102:105], v[158:161], v[186:189], v[102:105]
	v_mfma_i32_16x16x64_i8 v[94:97], v[146:149], v[190:193], v[94:97]
	v_mfma_i32_16x16x64_i8 v[94:97], v[150:153], v[200:203], v[94:97]
	v_mfma_i32_16x16x64_i8 v[90:93], v[154:157], v[190:193], v[90:93]
	v_mfma_i32_16x16x64_i8 v[90:93], v[158:161], v[200:203], v[90:93]
	v_mfma_i32_16x16x64_i8 v[86:89], v[146:149], v[204:207], v[86:89]
	v_mfma_i32_16x16x64_i8 v[86:89], v[150:153], v[208:211], v[86:89]
	v_mfma_i32_16x16x64_i8 v[82:85], v[154:157], v[204:207], v[82:85]
	v_mfma_i32_16x16x64_i8 v[82:85], v[158:161], v[208:211], v[82:85]
	s_barrier
	s_add_i32 s42, s42, s81
	v_lshl_add_u64 v[194:195], s[28:29], 0, v[164:165]
	s_mov_b32 m0, s42
	ds_read_b128 v[174:177], v250 offset:16384
	ds_read_b128 v[178:181], v250 offset:17408
	ds_read_b128 v[182:185], v250 offset:18432
	ds_read_b128 v[186:189], v250 offset:19456
	ds_read_b128 v[190:193], v250 offset:20480
	ds_read_b128 v[200:203], v250 offset:21504
	ds_read_b128 v[204:207], v250 offset:22528
	ds_read_b128 v[208:211], v250 offset:23552
	global_load_lds_dwordx4 v[194:195], off
	s_add_i32 m0, s42, 0x2000
	s_add_u32 s42, s28, 0x80000
	v_lshl_add_u64 v[212:213], s[28:29], 0, v[168:169]
	s_addc_u32 s43, s29, 0
	s_add_i32 s49, s49, s81
	global_load_lds_dwordx4 v[212:213], off
	v_lshl_add_u64 v[214:215], s[42:43], 0, v[164:165]
	s_mov_b32 m0, s49
	v_lshl_add_u64 v[216:217], s[30:31], 0, v[166:167]
	global_load_lds_dwordx4 v[214:215], off
	v_lshl_add_u64 v[214:215], s[42:43], 0, v[168:169]
	s_add_i32 m0, s49, 0x2000
	s_nop 0
	global_load_lds_dwordx4 v[214:215], off
	v_lshl_add_u64 v[214:215], s[30:31], 0, v[162:163]
	s_waitcnt vmcnt(6)
	s_waitcnt lgkmcnt(0)
	s_barrier
	s_waitcnt lgkmcnt(0)
	v_mfma_i32_16x16x64_i8 v[78:81], v[2:5], v[174:177], v[78:81]
	v_mfma_i32_16x16x64_i8 v[78:81], v[6:9], v[178:181], v[78:81]
	v_mfma_i32_16x16x64_i8 v[74:77], v[10:13], v[174:177], v[74:77]
	v_mfma_i32_16x16x64_i8 v[74:77], v[14:17], v[178:181], v[74:77]
	v_mfma_i32_16x16x64_i8 v[70:73], v[2:5], v[182:185], v[70:73]
	v_mfma_i32_16x16x64_i8 v[70:73], v[6:9], v[186:189], v[70:73]
	v_mfma_i32_16x16x64_i8 v[66:69], v[10:13], v[182:185], v[66:69]
	v_mfma_i32_16x16x64_i8 v[66:69], v[14:17], v[186:189], v[66:69]
	v_mfma_i32_16x16x64_i8 v[54:57], v[2:5], v[190:193], v[54:57]
	v_mfma_i32_16x16x64_i8 v[54:57], v[6:9], v[200:203], v[54:57]
	v_mfma_i32_16x16x64_i8 v[50:53], v[10:13], v[190:193], v[50:53]
	v_mfma_i32_16x16x64_i8 v[50:53], v[14:17], v[200:203], v[50:53]
	v_mfma_i32_16x16x64_i8 v[2:5], v[2:5], v[204:207], v[38:41]
	v_mfma_i32_16x16x64_i8 v[2:5], v[6:9], v[208:211], v[2:5]
	v_mfma_i32_16x16x64_i8 v[6:9], v[10:13], v[204:207], v[34:37]
	v_mfma_i32_16x16x64_i8 v[6:9], v[14:17], v[208:211], v[6:9]
	v_mfma_i32_16x16x64_i8 v[34:37], v[146:149], v[182:185], v[46:49]
	v_mfma_i32_16x16x64_i8 v[46:49], v[150:153], v[186:189], v[34:37]
	v_mfma_i32_16x16x64_i8 v[34:37], v[154:157], v[182:185], v[42:45]
	v_mfma_i32_16x16x64_i8 v[42:45], v[158:161], v[186:189], v[34:37]
	v_mfma_i32_16x16x64_i8 v[30:33], v[146:149], v[190:193], v[30:33]
	v_mfma_i32_16x16x64_i8 v[30:33], v[150:153], v[200:203], v[30:33]
	v_mfma_i32_16x16x64_i8 v[26:29], v[154:157], v[190:193], v[26:29]
	v_mfma_i32_16x16x64_i8 v[26:29], v[158:161], v[200:203], v[26:29]
	v_mfma_i32_16x16x64_i8 v[22:25], v[146:149], v[204:207], v[22:25]
	v_mfma_i32_16x16x64_i8 v[22:25], v[150:153], v[208:211], v[22:25]
	v_mfma_i32_16x16x64_i8 v[18:21], v[154:157], v[204:207], v[18:21]
	v_mfma_i32_16x16x64_i8 v[18:21], v[158:161], v[208:211], v[18:21]
	v_mfma_i32_16x16x64_i8 v[10:13], v[146:149], v[174:177], v[62:65]
	v_mfma_i32_16x16x64_i8 v[10:13], v[150:153], v[178:181], v[10:13]
	v_mfma_i32_16x16x64_i8 v[14:17], v[154:157], v[174:177], v[58:61]
	v_mfma_i32_16x16x64_i8 v[14:17], v[158:161], v[178:181], v[14:17]
	s_barrier
	s_add_i32 s42, 0, 0x18000
	v_add_u32_e32 v0, s42, v199
	s_add_i32 s43, 0, 0x1c000
	ds_read_b128 v[34:37], v0
	ds_read_b128 v[38:41], v0 offset:1024
	ds_read_b128 v[58:61], v0 offset:2048
	ds_read_b128 v[62:65], v0 offset:3072
	v_add_u32_e32 v0, s43, v199
	ds_read_b128 v[146:149], v0
	ds_read_b128 v[150:153], v0 offset:1024
	ds_read_b128 v[154:157], v0 offset:2048
	ds_read_b128 v[158:161], v0 offset:3072
	s_add_u32 s30, s30, 0x80000
	s_addc_u32 s31, s31, 0
	s_mov_b32 m0, s21
	v_lshl_add_u64 v[218:219], s[30:31], 0, v[162:163]
	ds_read_b128 v[174:177], v250 offset:32768
	ds_read_b128 v[178:181], v250 offset:33792
	ds_read_b128 v[182:185], v250 offset:34816
	ds_read_b128 v[186:189], v250 offset:35840
	ds_read_b128 v[190:193], v250 offset:36864
	ds_read_b128 v[200:203], v250 offset:37888
	ds_read_b128 v[204:207], v250 offset:38912
	ds_read_b128 v[208:211], v250 offset:39936
	global_load_lds_dwordx4 v[214:215], off
	s_mov_b32 m0, s57
	s_nop 0
	global_load_lds_dwordx4 v[216:217], off
	s_mov_b32 m0, s73
	s_nop 0
	global_load_lds_dwordx4 v[218:219], off
	v_lshl_add_u64 v[218:219], s[30:31], 0, v[166:167]
	s_mov_b32 m0, s76
	s_nop 0
	global_load_lds_dwordx4 v[218:219], off
	s_waitcnt vmcnt(8)
	s_waitcnt lgkmcnt(0)
	s_barrier
	s_waitcnt lgkmcnt(0)
	v_mfma_i32_16x16x64_i8 v[142:145], v[34:37], v[174:177], v[142:145]
	v_mfma_i32_16x16x64_i8 v[142:145], v[38:41], v[178:181], v[142:145]
	v_mfma_i32_16x16x64_i8 v[138:141], v[58:61], v[174:177], v[138:141]
	v_mfma_i32_16x16x64_i8 v[138:141], v[62:65], v[178:181], v[138:141]
	v_mfma_i32_16x16x64_i8 v[134:137], v[34:37], v[182:185], v[134:137]
	v_mfma_i32_16x16x64_i8 v[134:137], v[38:41], v[186:189], v[134:137]
	v_mfma_i32_16x16x64_i8 v[130:133], v[58:61], v[182:185], v[130:133]
	v_mfma_i32_16x16x64_i8 v[130:133], v[62:65], v[186:189], v[130:133]
	v_mfma_i32_16x16x64_i8 v[122:125], v[34:37], v[190:193], v[122:125]
	v_mfma_i32_16x16x64_i8 v[122:125], v[38:41], v[200:203], v[122:125]
	v_mfma_i32_16x16x64_i8 v[114:117], v[58:61], v[190:193], v[114:117]
	v_mfma_i32_16x16x64_i8 v[114:117], v[62:65], v[200:203], v[114:117]
	v_mfma_i32_16x16x64_i8 v[106:109], v[34:37], v[204:207], v[106:109]
	v_mfma_i32_16x16x64_i8 v[106:109], v[38:41], v[208:211], v[106:109]
	v_mfma_i32_16x16x64_i8 v[98:101], v[58:61], v[204:207], v[98:101]
	v_mfma_i32_16x16x64_i8 v[98:101], v[62:65], v[208:211], v[98:101]
	v_mfma_i32_16x16x64_i8 v[126:129], v[146:149], v[174:177], v[126:129]
	v_mfma_i32_16x16x64_i8 v[126:129], v[150:153], v[178:181], v[126:129]
	v_mfma_i32_16x16x64_i8 v[118:121], v[154:157], v[174:177], v[118:121]
	v_mfma_i32_16x16x64_i8 v[118:121], v[158:161], v[178:181], v[118:121]
	v_mfma_i32_16x16x64_i8 v[110:113], v[146:149], v[182:185], v[110:113]
	v_mfma_i32_16x16x64_i8 v[110:113], v[150:153], v[186:189], v[110:113]
	v_mfma_i32_16x16x64_i8 v[102:105], v[154:157], v[182:185], v[102:105]
	v_mfma_i32_16x16x64_i8 v[102:105], v[158:161], v[186:189], v[102:105]
	v_mfma_i32_16x16x64_i8 v[94:97], v[146:149], v[190:193], v[94:97]
	v_mfma_i32_16x16x64_i8 v[94:97], v[150:153], v[200:203], v[94:97]
	v_mfma_i32_16x16x64_i8 v[90:93], v[154:157], v[190:193], v[90:93]
	v_mfma_i32_16x16x64_i8 v[90:93], v[158:161], v[200:203], v[90:93]
	v_mfma_i32_16x16x64_i8 v[86:89], v[146:149], v[204:207], v[86:89]
	v_mfma_i32_16x16x64_i8 v[86:89], v[150:153], v[208:211], v[86:89]
	v_mfma_i32_16x16x64_i8 v[82:85], v[154:157], v[204:207], v[82:85]
	v_mfma_i32_16x16x64_i8 v[82:85], v[158:161], v[208:211], v[82:85]
	s_barrier
	s_add_i32 s30, s42, s81
	v_lshl_add_u64 v[194:195], v[194:195], 0, s[12:13]
	s_mov_b32 m0, s30
	ds_read_b128 v[174:177], v250 offset:49152
	ds_read_b128 v[178:181], v250 offset:50176
	ds_read_b128 v[182:185], v250 offset:51200
	ds_read_b128 v[186:189], v250 offset:52224
	ds_read_b128 v[190:193], v250 offset:53248
	ds_read_b128 v[200:203], v250 offset:54272
	ds_read_b128 v[204:207], v250 offset:55296
	ds_read_b128 v[208:211], v250 offset:56320
	global_load_lds_dwordx4 v[194:195], off
	s_add_i32 m0, s30, 0x2000
	s_add_u32 s28, s28, 0x80080
	v_lshl_add_u64 v[194:195], v[212:213], 0, s[12:13]
	s_addc_u32 s29, s29, 0
	s_add_i32 s30, s43, s81
	global_load_lds_dwordx4 v[194:195], off
	v_lshl_add_u64 v[194:195], s[28:29], 0, v[164:165]
	s_mov_b32 m0, s30
	s_nop 0
	global_load_lds_dwordx4 v[194:195], off
	v_lshl_add_u64 v[194:195], s[28:29], 0, v[168:169]
	s_add_i32 m0, s30, 0x2000
	s_nop 0
	global_load_lds_dwordx4 v[194:195], off
	s_waitcnt vmcnt(6)
	s_waitcnt lgkmcnt(0)
	s_barrier
	s_waitcnt lgkmcnt(0)
	v_mfma_i32_16x16x64_i8 v[78:81], v[34:37], v[174:177], v[78:81]
	v_mfma_i32_16x16x64_i8 v[78:81], v[38:41], v[178:181], v[78:81]
	v_mfma_i32_16x16x64_i8 v[70:73], v[34:37], v[182:185], v[70:73]
	v_mfma_i32_16x16x64_i8 v[70:73], v[38:41], v[186:189], v[70:73]
	v_mfma_i32_16x16x64_i8 v[54:57], v[34:37], v[190:193], v[54:57]
	v_mfma_i32_16x16x64_i8 v[54:57], v[38:41], v[200:203], v[54:57]
	v_mfma_i32_16x16x64_i8 v[2:5], v[34:37], v[204:207], v[2:5]
	v_mfma_i32_16x16x64_i8 v[38:41], v[38:41], v[208:211], v[2:5]
	v_mfma_i32_16x16x64_i8 v[74:77], v[58:61], v[174:177], v[74:77]
	v_mfma_i32_16x16x64_i8 v[74:77], v[62:65], v[178:181], v[74:77]
	v_mfma_i32_16x16x64_i8 v[66:69], v[58:61], v[182:185], v[66:69]
	v_mfma_i32_16x16x64_i8 v[66:69], v[62:65], v[186:189], v[66:69]
	v_mfma_i32_16x16x64_i8 v[50:53], v[58:61], v[190:193], v[50:53]
	v_mfma_i32_16x16x64_i8 v[50:53], v[62:65], v[200:203], v[50:53]
	v_mfma_i32_16x16x64_i8 v[2:5], v[58:61], v[204:207], v[6:9]
	v_mfma_i32_16x16x64_i8 v[34:37], v[62:65], v[208:211], v[2:5]
	v_mfma_i32_16x16x64_i8 v[2:5], v[146:149], v[174:177], v[10:13]
	v_mfma_i32_16x16x64_i8 v[62:65], v[150:153], v[178:181], v[2:5]
	v_mfma_i32_16x16x64_i8 v[2:5], v[154:157], v[174:177], v[14:17]
	v_mfma_i32_16x16x64_i8 v[58:61], v[158:161], v[178:181], v[2:5]
	v_mfma_i32_16x16x64_i8 v[2:5], v[146:149], v[182:185], v[46:49]
	v_mfma_i32_16x16x64_i8 v[46:49], v[150:153], v[186:189], v[2:5]
	v_mfma_i32_16x16x64_i8 v[2:5], v[154:157], v[182:185], v[42:45]
	v_mfma_i32_16x16x64_i8 v[42:45], v[158:161], v[186:189], v[2:5]
	v_mfma_i32_16x16x64_i8 v[2:5], v[146:149], v[190:193], v[30:33]
	v_mfma_i32_16x16x64_i8 v[30:33], v[150:153], v[200:203], v[2:5]
	v_mfma_i32_16x16x64_i8 v[2:5], v[154:157], v[190:193], v[26:29]
	v_mfma_i32_16x16x64_i8 v[26:29], v[158:161], v[200:203], v[2:5]
	v_mfma_i32_16x16x64_i8 v[2:5], v[146:149], v[204:207], v[22:25]
	v_mfma_i32_16x16x64_i8 v[22:25], v[150:153], v[208:211], v[2:5]
	v_mfma_i32_16x16x64_i8 v[2:5], v[154:157], v[204:207], v[18:21]
	v_mfma_i32_16x16x64_i8 v[18:21], v[158:161], v[208:211], v[2:5]
	s_barrier
	s_add_i32 s41, s41, 2
	s_add_u32 s0, s0, 0x100
	s_addc_u32 s1, s1, 0
	s_add_u32 s35, s35, 0x100
	s_addc_u32 s40, s40, 0
	s_cmp_gt_u32 s41, 29
	s_cbranch_scc0 .LBB0_300
	s_and_b64 vcc, exec, s[52:53]
	s_cbranch_vccz .LBB0_303
	s_barrier

.LBB0_577:
	s_add_u32 s34, s30, 0xfff80080
	s_addc_u32 s35, s31, -1
	s_add_i32 s66, 0, 0x10000
	s_cmp_eq_u32 s57, 28
	s_cselect_b32 s43, s19, s35
	s_cselect_b32 s42, s23, s34
	v_add_u32_e32 v0, s66, v228
	s_cselect_b32 s35, s25, s56
	s_cselect_b32 s34, s54, s55
	s_add_i32 s73, 0, 0x14000
	ds_read_b128 v[132:135], v0
	ds_read_b128 v[136:139], v0 offset:1024
	ds_read_b128 v[140:143], v0 offset:2048
	ds_read_b128 v[144:147], v0 offset:3072
	v_add_u32_e32 v0, s73, v228
	ds_read_b128 v[148:151], v0
	ds_read_b128 v[152:155], v0 offset:1024
	ds_read_b128 v[156:159], v0 offset:2048
	ds_read_b128 v[160:163], v0 offset:3072
	v_lshl_add_u64 v[2:3], s[30:31], 0, v[208:209]
	s_add_i32 m0, s46, 0xc000
	ds_read_b128 v[164:167], v230
	ds_read_b128 v[168:171], v230 offset:1024
	ds_read_b128 v[172:175], v230 offset:2048
	ds_read_b128 v[176:179], v230 offset:3072
	ds_read_b128 v[180:183], v230 offset:4096
	ds_read_b128 v[184:187], v230 offset:5120
	ds_read_b128 v[188:191], v230 offset:6144
	ds_read_b128 v[192:195], v230 offset:7168
	global_load_lds_dwordx4 v[2:3], off
	v_lshl_add_u64 v[2:3], s[30:31], 0, v[210:211]
	s_add_i32 m0, s46, 0xe000
	s_nop 0
	global_load_lds_dwordx4 v[2:3], off
	s_waitcnt vmcnt(8)
	s_waitcnt lgkmcnt(0)
	s_barrier
	s_waitcnt lgkmcnt(0)
	v_mfma_f32_16x16x32_bf16 v[128:131], v[132:135], v[164:167], v[128:131]
	v_mfma_f32_16x16x32_bf16 v[128:131], v[136:139], v[168:171], v[128:131]
	v_mfma_f32_16x16x32_bf16 v[124:127], v[140:143], v[164:167], v[124:127]
	v_mfma_f32_16x16x32_bf16 v[124:127], v[144:147], v[168:171], v[124:127]
	v_mfma_f32_16x16x32_bf16 v[120:123], v[132:135], v[172:175], v[120:123]
	v_mfma_f32_16x16x32_bf16 v[120:123], v[136:139], v[176:179], v[120:123]
	v_mfma_f32_16x16x32_bf16 v[116:119], v[140:143], v[172:175], v[116:119]
	v_mfma_f32_16x16x32_bf16 v[116:119], v[144:147], v[176:179], v[116:119]
	v_mfma_f32_16x16x32_bf16 v[112:115], v[132:135], v[180:183], v[112:115]
	v_mfma_f32_16x16x32_bf16 v[112:115], v[136:139], v[184:187], v[112:115]
	v_mfma_f32_16x16x32_bf16 v[108:111], v[140:143], v[180:183], v[108:111]
	v_mfma_f32_16x16x32_bf16 v[108:111], v[144:147], v[184:187], v[108:111]
	v_mfma_f32_16x16x32_bf16 v[104:107], v[132:135], v[188:191], v[104:107]
	v_mfma_f32_16x16x32_bf16 v[104:107], v[136:139], v[192:195], v[104:107]
	v_mfma_f32_16x16x32_bf16 v[100:103], v[140:143], v[188:191], v[100:103]
	v_mfma_f32_16x16x32_bf16 v[100:103], v[144:147], v[192:195], v[100:103]
	v_mfma_f32_16x16x32_bf16 v[96:99], v[148:151], v[164:167], v[96:99]
	v_mfma_f32_16x16x32_bf16 v[96:99], v[152:155], v[168:171], v[96:99]
	v_mfma_f32_16x16x32_bf16 v[92:95], v[156:159], v[164:167], v[92:95]
	v_mfma_f32_16x16x32_bf16 v[92:95], v[160:163], v[168:171], v[92:95]
	v_mfma_f32_16x16x32_bf16 v[88:91], v[148:151], v[172:175], v[88:91]
	v_mfma_f32_16x16x32_bf16 v[88:91], v[152:155], v[176:179], v[88:91]
	v_mfma_f32_16x16x32_bf16 v[84:87], v[156:159], v[172:175], v[84:87]
	v_mfma_f32_16x16x32_bf16 v[84:87], v[160:163], v[176:179], v[84:87]
	v_mfma_f32_16x16x32_bf16 v[80:83], v[148:151], v[180:183], v[80:83]
	v_mfma_f32_16x16x32_bf16 v[80:83], v[152:155], v[184:187], v[80:83]
	v_mfma_f32_16x16x32_bf16 v[76:79], v[156:159], v[180:183], v[76:79]
	v_mfma_f32_16x16x32_bf16 v[76:79], v[160:163], v[184:187], v[76:79]
	v_mfma_f32_16x16x32_bf16 v[72:75], v[148:151], v[188:191], v[72:75]
	v_mfma_f32_16x16x32_bf16 v[72:75], v[152:155], v[192:195], v[72:75]
	v_mfma_f32_16x16x32_bf16 v[68:71], v[156:159], v[188:191], v[68:71]
	v_mfma_f32_16x16x32_bf16 v[68:71], v[160:163], v[192:195], v[68:71]
	s_barrier
	s_add_i32 s66, s66, s15
	v_lshl_add_u64 v[212:213], s[34:35], 0, v[204:205]
	s_mov_b32 m0, s66
	ds_read_b128 v[164:167], v230 offset:16384
	ds_read_b128 v[168:171], v230 offset:17408
	ds_read_b128 v[172:175], v230 offset:18432
	ds_read_b128 v[176:179], v230 offset:19456
	ds_read_b128 v[180:183], v230 offset:20480
	ds_read_b128 v[184:187], v230 offset:21504
	ds_read_b128 v[188:191], v230 offset:22528
	ds_read_b128 v[192:195], v230 offset:23552
	global_load_lds_dwordx4 v[212:213], off
	s_add_i32 m0, s66, 0x2000
	s_add_u32 s66, s34, 0x80000
	v_lshl_add_u64 v[214:215], s[34:35], 0, v[200:201]
	s_addc_u32 s67, s35, 0
	s_add_i32 s73, s73, s15
	global_load_lds_dwordx4 v[214:215], off
	v_lshl_add_u64 v[2:3], s[66:67], 0, v[204:205]
	s_mov_b32 m0, s73
	v_lshl_add_u64 v[216:217], s[42:43], 0, v[206:207]
	global_load_lds_dwordx4 v[2:3], off
	v_lshl_add_u64 v[2:3], s[66:67], 0, v[200:201]
	s_add_i32 m0, s73, 0x2000
	v_lshl_add_u64 v[218:219], s[42:43], 0, v[202:203]
	global_load_lds_dwordx4 v[2:3], off
	s_mov_b32 m0, s46
	s_nop 0
	global_load_lds_dwordx4 v[216:217], off
	s_mov_b32 m0, s47
	s_nop 0
	global_load_lds_dwordx4 v[218:219], off
	s_waitcnt vmcnt(8)
	s_waitcnt lgkmcnt(0)
	s_barrier
	s_waitcnt lgkmcnt(0)
	v_mfma_f32_16x16x32_bf16 v[64:67], v[132:135], v[164:167], v[64:67]
	v_mfma_f32_16x16x32_bf16 v[64:67], v[136:139], v[168:171], v[64:67]
	v_mfma_f32_16x16x32_bf16 v[60:63], v[140:143], v[164:167], v[60:63]
	v_mfma_f32_16x16x32_bf16 v[60:63], v[144:147], v[168:171], v[60:63]
	v_mfma_f32_16x16x32_bf16 v[56:59], v[132:135], v[172:175], v[56:59]
	v_mfma_f32_16x16x32_bf16 v[56:59], v[136:139], v[176:179], v[56:59]
	v_mfma_f32_16x16x32_bf16 v[52:55], v[140:143], v[172:175], v[52:55]
	v_mfma_f32_16x16x32_bf16 v[52:55], v[144:147], v[176:179], v[52:55]
	v_mfma_f32_16x16x32_bf16 v[48:51], v[132:135], v[180:183], v[48:51]
	v_mfma_f32_16x16x32_bf16 v[48:51], v[136:139], v[184:187], v[48:51]
	v_mfma_f32_16x16x32_bf16 v[44:47], v[140:143], v[180:183], v[44:47]
	v_mfma_f32_16x16x32_bf16 v[44:47], v[144:147], v[184:187], v[44:47]
	v_mfma_f32_16x16x32_bf16 v[40:43], v[132:135], v[188:191], v[40:43]
	v_mfma_f32_16x16x32_bf16 v[40:43], v[136:139], v[192:195], v[40:43]
	v_mfma_f32_16x16x32_bf16 v[36:39], v[140:143], v[188:191], v[36:39]
	v_mfma_f32_16x16x32_bf16 v[36:39], v[144:147], v[192:195], v[36:39]
	v_mfma_f32_16x16x32_bf16 v[32:35], v[148:151], v[164:167], v[32:35]
	v_mfma_f32_16x16x32_bf16 v[32:35], v[152:155], v[168:171], v[32:35]
	v_mfma_f32_16x16x32_bf16 v[28:31], v[156:159], v[164:167], v[28:31]
	v_mfma_f32_16x16x32_bf16 v[28:31], v[160:163], v[168:171], v[28:31]
	v_mfma_f32_16x16x32_bf16 v[24:27], v[148:151], v[172:175], v[24:27]
	v_mfma_f32_16x16x32_bf16 v[24:27], v[152:155], v[176:179], v[24:27]
	v_mfma_f32_16x16x32_bf16 v[20:23], v[156:159], v[172:175], v[20:23]
	v_mfma_f32_16x16x32_bf16 v[20:23], v[160:163], v[176:179], v[20:23]
	v_mfma_f32_16x16x32_bf16 v[16:19], v[148:151], v[180:183], v[16:19]
	v_mfma_f32_16x16x32_bf16 v[16:19], v[152:155], v[184:187], v[16:19]
	v_mfma_f32_16x16x32_bf16 v[12:15], v[156:159], v[180:183], v[12:15]
	v_mfma_f32_16x16x32_bf16 v[12:15], v[160:163], v[184:187], v[12:15]
	v_mfma_f32_16x16x32_bf16 v[8:11], v[148:151], v[188:191], v[8:11]
	v_mfma_f32_16x16x32_bf16 v[8:11], v[152:155], v[192:195], v[8:11]
	v_mfma_f32_16x16x32_bf16 v[2:5], v[156:159], v[188:191], v[4:7]
	v_mfma_f32_16x16x32_bf16 v[2:5], v[160:163], v[192:195], v[2:5]
	s_barrier
	s_add_i32 s66, 0, 0x18000
	v_add_u32_e32 v0, s66, v228
	s_add_i32 s67, 0, 0x1c000
	ds_read_b128 v[132:135], v0
	ds_read_b128 v[136:139], v0 offset:1024
	ds_read_b128 v[140:143], v0 offset:2048
	ds_read_b128 v[144:147], v0 offset:3072
	v_add_u32_e32 v0, s67, v228
	ds_read_b128 v[148:151], v0
	ds_read_b128 v[152:155], v0 offset:1024
	ds_read_b128 v[156:159], v0 offset:2048
	ds_read_b128 v[160:163], v0 offset:3072
	s_add_u32 s42, s42, 0x80000
	s_addc_u32 s43, s43, 0
	s_mov_b32 m0, s48
	v_lshl_add_u64 v[6:7], s[42:43], 0, v[206:207]
	ds_read_b128 v[164:167], v230 offset:32768
	ds_read_b128 v[168:171], v230 offset:33792
	ds_read_b128 v[172:175], v230 offset:34816
	ds_read_b128 v[176:179], v230 offset:35840
	ds_read_b128 v[180:183], v230 offset:36864
	ds_read_b128 v[184:187], v230 offset:37888
	ds_read_b128 v[188:191], v230 offset:38912
	ds_read_b128 v[192:195], v230 offset:39936
	global_load_lds_dwordx4 v[6:7], off
	v_lshl_add_u64 v[6:7], s[42:43], 0, v[202:203]
	s_mov_b32 m0, s49
	s_nop 0
	global_load_lds_dwordx4 v[6:7], off
	s_waitcnt vmcnt(8)
	s_waitcnt lgkmcnt(0)
	s_barrier
	s_waitcnt lgkmcnt(0)
	v_mfma_f32_16x16x32_bf16 v[128:131], v[132:135], v[164:167], v[128:131]
	v_mfma_f32_16x16x32_bf16 v[128:131], v[136:139], v[168:171], v[128:131]
	v_mfma_f32_16x16x32_bf16 v[124:127], v[140:143], v[164:167], v[124:127]
	v_mfma_f32_16x16x32_bf16 v[124:127], v[144:147], v[168:171], v[124:127]
	v_mfma_f32_16x16x32_bf16 v[120:123], v[132:135], v[172:175], v[120:123]
	v_mfma_f32_16x16x32_bf16 v[120:123], v[136:139], v[176:179], v[120:123]
	v_mfma_f32_16x16x32_bf16 v[116:119], v[140:143], v[172:175], v[116:119]
	v_mfma_f32_16x16x32_bf16 v[116:119], v[144:147], v[176:179], v[116:119]
	v_mfma_f32_16x16x32_bf16 v[112:115], v[132:135], v[180:183], v[112:115]
	v_mfma_f32_16x16x32_bf16 v[112:115], v[136:139], v[184:187], v[112:115]
	v_mfma_f32_16x16x32_bf16 v[108:111], v[140:143], v[180:183], v[108:111]
	v_mfma_f32_16x16x32_bf16 v[108:111], v[144:147], v[184:187], v[108:111]
	v_mfma_f32_16x16x32_bf16 v[104:107], v[132:135], v[188:191], v[104:107]
	v_mfma_f32_16x16x32_bf16 v[104:107], v[136:139], v[192:195], v[104:107]
	v_mfma_f32_16x16x32_bf16 v[100:103], v[140:143], v[188:191], v[100:103]
	v_mfma_f32_16x16x32_bf16 v[100:103], v[144:147], v[192:195], v[100:103]
	v_mfma_f32_16x16x32_bf16 v[96:99], v[148:151], v[164:167], v[96:99]
	v_mfma_f32_16x16x32_bf16 v[96:99], v[152:155], v[168:171], v[96:99]
	v_mfma_f32_16x16x32_bf16 v[92:95], v[156:159], v[164:167], v[92:95]
	v_mfma_f32_16x16x32_bf16 v[92:95], v[160:163], v[168:171], v[92:95]
	v_mfma_f32_16x16x32_bf16 v[88:91], v[148:151], v[172:175], v[88:91]
	v_mfma_f32_16x16x32_bf16 v[88:91], v[152:155], v[176:179], v[88:91]
	v_mfma_f32_16x16x32_bf16 v[84:87], v[156:159], v[172:175], v[84:87]
	v_mfma_f32_16x16x32_bf16 v[84:87], v[160:163], v[176:179], v[84:87]
	v_mfma_f32_16x16x32_bf16 v[80:83], v[148:151], v[180:183], v[80:83]
	v_mfma_f32_16x16x32_bf16 v[80:83], v[152:155], v[184:187], v[80:83]
	v_mfma_f32_16x16x32_bf16 v[76:79], v[156:159], v[180:183], v[76:79]
	v_mfma_f32_16x16x32_bf16 v[76:79], v[160:163], v[184:187], v[76:79]
	v_mfma_f32_16x16x32_bf16 v[72:75], v[148:151], v[188:191], v[72:75]
	v_mfma_f32_16x16x32_bf16 v[72:75], v[152:155], v[192:195], v[72:75]
	v_mfma_f32_16x16x32_bf16 v[68:71], v[156:159], v[188:191], v[68:71]
	v_mfma_f32_16x16x32_bf16 v[68:71], v[160:163], v[192:195], v[68:71]
	s_barrier
	s_add_i32 s42, s66, s15
	v_lshl_add_u64 v[6:7], v[212:213], 0, s[12:13]
	s_mov_b32 m0, s42
	ds_read_b128 v[164:167], v230 offset:49152
	ds_read_b128 v[168:171], v230 offset:50176
	ds_read_b128 v[172:175], v230 offset:51200
	ds_read_b128 v[176:179], v230 offset:52224
	ds_read_b128 v[180:183], v230 offset:53248
	ds_read_b128 v[184:187], v230 offset:54272
	ds_read_b128 v[188:191], v230 offset:55296
	ds_read_b128 v[192:195], v230 offset:56320
	global_load_lds_dwordx4 v[6:7], off
	s_add_i32 m0, s42, 0x2000
	s_add_u32 s34, s34, 0x80080
	v_lshl_add_u64 v[6:7], v[214:215], 0, s[12:13]
	s_addc_u32 s35, s35, 0
	s_add_i32 s42, s67, s15
	global_load_lds_dwordx4 v[6:7], off
	v_lshl_add_u64 v[6:7], s[34:35], 0, v[204:205]
	s_mov_b32 m0, s42
	s_nop 0
	global_load_lds_dwordx4 v[6:7], off
	v_lshl_add_u64 v[6:7], s[34:35], 0, v[200:201]
	s_add_i32 m0, s42, 0x2000
	s_nop 0
	global_load_lds_dwordx4 v[6:7], off
	v_lshl_add_u64 v[6:7], v[216:217], 0, s[12:13]
	s_mov_b32 m0, s50
	s_nop 0
	global_load_lds_dwordx4 v[6:7], off
	v_lshl_add_u64 v[6:7], v[218:219], 0, s[12:13]
	s_mov_b32 m0, s51
	s_nop 0
	global_load_lds_dwordx4 v[6:7], off
	s_waitcnt vmcnt(8)
	s_waitcnt lgkmcnt(0)
	s_barrier
	s_waitcnt lgkmcnt(0)
	v_mfma_f32_16x16x32_bf16 v[64:67], v[132:135], v[164:167], v[64:67]
	v_mfma_f32_16x16x32_bf16 v[64:67], v[136:139], v[168:171], v[64:67]
	v_mfma_f32_16x16x32_bf16 v[60:63], v[140:143], v[164:167], v[60:63]
	v_mfma_f32_16x16x32_bf16 v[60:63], v[144:147], v[168:171], v[60:63]
	v_mfma_f32_16x16x32_bf16 v[56:59], v[132:135], v[172:175], v[56:59]
	v_mfma_f32_16x16x32_bf16 v[56:59], v[136:139], v[176:179], v[56:59]
	v_mfma_f32_16x16x32_bf16 v[52:55], v[140:143], v[172:175], v[52:55]
	v_mfma_f32_16x16x32_bf16 v[52:55], v[144:147], v[176:179], v[52:55]
	v_mfma_f32_16x16x32_bf16 v[48:51], v[132:135], v[180:183], v[48:51]
	v_mfma_f32_16x16x32_bf16 v[48:51], v[136:139], v[184:187], v[48:51]
	v_mfma_f32_16x16x32_bf16 v[44:47], v[140:143], v[180:183], v[44:47]
	v_mfma_f32_16x16x32_bf16 v[44:47], v[144:147], v[184:187], v[44:47]
	v_mfma_f32_16x16x32_bf16 v[40:43], v[132:135], v[188:191], v[40:43]
	v_mfma_f32_16x16x32_bf16 v[40:43], v[136:139], v[192:195], v[40:43]
	v_mfma_f32_16x16x32_bf16 v[36:39], v[140:143], v[188:191], v[36:39]
	v_mfma_f32_16x16x32_bf16 v[36:39], v[144:147], v[192:195], v[36:39]
	v_mfma_f32_16x16x32_bf16 v[32:35], v[148:151], v[164:167], v[32:35]
	v_mfma_f32_16x16x32_bf16 v[32:35], v[152:155], v[168:171], v[32:35]
	v_mfma_f32_16x16x32_bf16 v[28:31], v[156:159], v[164:167], v[28:31]
	v_mfma_f32_16x16x32_bf16 v[28:31], v[160:163], v[168:171], v[28:31]
	v_mfma_f32_16x16x32_bf16 v[24:27], v[148:151], v[172:175], v[24:27]
	v_mfma_f32_16x16x32_bf16 v[24:27], v[152:155], v[176:179], v[24:27]
	v_mfma_f32_16x16x32_bf16 v[20:23], v[156:159], v[172:175], v[20:23]
	v_mfma_f32_16x16x32_bf16 v[20:23], v[160:163], v[176:179], v[20:23]
	v_mfma_f32_16x16x32_bf16 v[16:19], v[148:151], v[180:183], v[16:19]
	v_mfma_f32_16x16x32_bf16 v[16:19], v[152:155], v[184:187], v[16:19]
	v_mfma_f32_16x16x32_bf16 v[12:15], v[156:159], v[180:183], v[12:15]
	v_mfma_f32_16x16x32_bf16 v[12:15], v[160:163], v[184:187], v[12:15]
	v_mfma_f32_16x16x32_bf16 v[6:9], v[148:151], v[188:191], v[8:11]
	v_mfma_f32_16x16x32_bf16 v[8:11], v[152:155], v[192:195], v[6:9]
	v_mfma_f32_16x16x32_bf16 v[2:5], v[156:159], v[188:191], v[2:5]
	v_mfma_f32_16x16x32_bf16 v[4:7], v[160:163], v[192:195], v[2:5]
	s_barrier
	s_add_i32 s57, s57, 2
	s_add_u32 s30, s30, 0x100
	s_addc_u32 s31, s31, 0
	s_add_u32 s55, s55, 0x100
	s_addc_u32 s56, s56, 0
	s_cmp_gt_u32 s57, 29
	s_cbranch_scc0 .LBB0_577
	s_and_b64 vcc, exec, s[20:21]
	s_cbranch_vccz .LBB0_580
	s_barrier

.LBB0_779:
	s_add_u32 s34, s30, 0xfff80080
	s_addc_u32 s35, s31, -1
	s_add_i32 s66, 0, 0x10000
	s_cmp_eq_u32 s57, 28
	s_cselect_b32 s43, s25, s35
	s_cselect_b32 s42, s53, s34
	s_cselect_b32 s35, s23, s56
	s_cselect_b32 s34, s54, s55
	s_add_i32 s73, 0, 0x14000
	v_add_u32_e32 v114, s66, v157
	v_add_u32_e32 v156, s73, v157
	ds_read_b128 v[90:93], v114
	ds_read_b128 v[94:97], v114 offset:1024
	ds_read_b128 v[106:109], v114 offset:2048
	ds_read_b128 v[114:117], v114 offset:3072
	ds_read_b128 v[162:165], v156
	ds_read_b128 v[166:169], v156 offset:1024
	ds_read_b128 v[170:173], v156 offset:2048
	ds_read_b128 v[174:177], v156 offset:3072
	v_lshl_add_u64 v[158:159], s[30:31], 0, v[152:153]
	s_add_i32 m0, s14, 0xc000
	ds_read_b128 v[178:181], v161
	ds_read_b128 v[182:185], v161 offset:1024
	ds_read_b128 v[186:189], v161 offset:2048
	ds_read_b128 v[190:193], v161 offset:3072
	ds_read_b128 v[200:203], v161 offset:4096
	ds_read_b128 v[204:207], v161 offset:5120
	ds_read_b128 v[208:211], v161 offset:6144
	ds_read_b128 v[212:215], v161 offset:7168
	global_load_lds_dwordx4 v[158:159], off
	v_lshl_add_u64 v[158:159], s[30:31], 0, v[154:155]
	s_add_i32 m0, s14, 0xe000
	s_nop 0
	global_load_lds_dwordx4 v[158:159], off
	s_waitcnt vmcnt(8)
	s_waitcnt lgkmcnt(0)
	s_barrier
	s_waitcnt lgkmcnt(0)
	v_mfma_i32_16x16x64_i8 v[142:145], v[90:93], v[178:181], v[142:145]
	v_mfma_i32_16x16x64_i8 v[142:145], v[94:97], v[182:185], v[142:145]
	v_mfma_i32_16x16x64_i8 v[138:141], v[106:109], v[178:181], v[138:141]
	v_mfma_i32_16x16x64_i8 v[138:141], v[114:117], v[182:185], v[138:141]
	v_mfma_i32_16x16x64_i8 v[126:129], v[90:93], v[186:189], v[126:129]
	v_mfma_i32_16x16x64_i8 v[126:129], v[94:97], v[190:193], v[126:129]
	v_mfma_i32_16x16x64_i8 v[122:125], v[106:109], v[186:189], v[122:125]
	v_mfma_i32_16x16x64_i8 v[122:125], v[114:117], v[190:193], v[122:125]
	v_mfma_i32_16x16x64_i8 v[102:105], v[90:93], v[200:203], v[102:105]
	v_mfma_i32_16x16x64_i8 v[102:105], v[94:97], v[204:207], v[102:105]
	v_mfma_i32_16x16x64_i8 v[98:101], v[106:109], v[200:203], v[98:101]
	v_mfma_i32_16x16x64_i8 v[98:101], v[114:117], v[204:207], v[98:101]
	v_mfma_i32_16x16x64_i8 v[78:81], v[90:93], v[208:211], v[78:81]
	v_mfma_i32_16x16x64_i8 v[78:81], v[94:97], v[212:215], v[78:81]
	v_mfma_i32_16x16x64_i8 v[74:77], v[106:109], v[208:211], v[74:77]
	v_mfma_i32_16x16x64_i8 v[74:77], v[114:117], v[212:215], v[74:77]
	v_mfma_i32_16x16x64_i8 v[134:137], v[162:165], v[178:181], v[134:137]
	v_mfma_i32_16x16x64_i8 v[134:137], v[166:169], v[182:185], v[134:137]
	v_mfma_i32_16x16x64_i8 v[130:133], v[170:173], v[178:181], v[130:133]
	v_mfma_i32_16x16x64_i8 v[130:133], v[174:177], v[182:185], v[130:133]
	v_mfma_i32_16x16x64_i8 v[118:121], v[162:165], v[186:189], v[118:121]
	v_mfma_i32_16x16x64_i8 v[118:121], v[166:169], v[190:193], v[118:121]
	v_mfma_i32_16x16x64_i8 v[110:113], v[170:173], v[186:189], v[110:113]
	v_mfma_i32_16x16x64_i8 v[110:113], v[174:177], v[190:193], v[110:113]
	v_mfma_i32_16x16x64_i8 v[86:89], v[162:165], v[200:203], v[86:89]
	v_mfma_i32_16x16x64_i8 v[86:89], v[166:169], v[204:207], v[86:89]
	v_mfma_i32_16x16x64_i8 v[82:85], v[170:173], v[200:203], v[82:85]
	v_mfma_i32_16x16x64_i8 v[82:85], v[174:177], v[204:207], v[82:85]
	v_mfma_i32_16x16x64_i8 v[70:73], v[162:165], v[208:211], v[70:73]
	v_mfma_i32_16x16x64_i8 v[70:73], v[166:169], v[212:215], v[70:73]
	v_mfma_i32_16x16x64_i8 v[66:69], v[170:173], v[208:211], v[66:69]
	v_mfma_i32_16x16x64_i8 v[66:69], v[174:177], v[212:215], v[66:69]
	s_barrier
	s_add_i32 s66, s66, s9
	v_lshl_add_u64 v[158:159], s[34:35], 0, v[0:1]
	s_mov_b32 m0, s66
	ds_read_b128 v[178:181], v161 offset:16384
	ds_read_b128 v[182:185], v161 offset:17408
	ds_read_b128 v[186:189], v161 offset:18432
	ds_read_b128 v[190:193], v161 offset:19456
	ds_read_b128 v[200:203], v161 offset:20480
	ds_read_b128 v[204:207], v161 offset:21504
	ds_read_b128 v[208:211], v161 offset:22528
	ds_read_b128 v[212:215], v161 offset:23552
	global_load_lds_dwordx4 v[158:159], off
	s_add_i32 m0, s66, 0x2000
	s_add_u32 s66, s34, 0x80000
	v_lshl_add_u64 v[194:195], s[34:35], 0, v[146:147]
	s_addc_u32 s67, s35, 0
	s_add_i32 s73, s73, s9
	global_load_lds_dwordx4 v[194:195], off
	v_lshl_add_u64 v[216:217], s[66:67], 0, v[0:1]
	s_mov_b32 m0, s73
	v_lshl_add_u64 v[218:219], s[42:43], 0, v[148:149]
	global_load_lds_dwordx4 v[216:217], off
	v_lshl_add_u64 v[216:217], s[66:67], 0, v[146:147]
	s_add_i32 m0, s73, 0x2000
	s_nop 0
	global_load_lds_dwordx4 v[216:217], off
	v_lshl_add_u64 v[216:217], s[42:43], 0, v[150:151]
	s_mov_b32 m0, s14
	s_nop 0
	global_load_lds_dwordx4 v[216:217], off
	s_mov_b32 m0, s15
	s_nop 0
	global_load_lds_dwordx4 v[218:219], off
	s_waitcnt vmcnt(8)
	s_waitcnt lgkmcnt(0)
	s_barrier
	s_waitcnt lgkmcnt(0)
	v_mfma_i32_16x16x64_i8 v[62:65], v[90:93], v[178:181], v[62:65]
	v_mfma_i32_16x16x64_i8 v[62:65], v[94:97], v[182:185], v[62:65]
	v_mfma_i32_16x16x64_i8 v[58:61], v[106:109], v[178:181], v[58:61]
	v_mfma_i32_16x16x64_i8 v[58:61], v[114:117], v[182:185], v[58:61]
	v_mfma_i32_16x16x64_i8 v[46:49], v[90:93], v[186:189], v[46:49]
	v_mfma_i32_16x16x64_i8 v[46:49], v[94:97], v[190:193], v[46:49]
	v_mfma_i32_16x16x64_i8 v[42:45], v[106:109], v[186:189], v[42:45]
	v_mfma_i32_16x16x64_i8 v[42:45], v[114:117], v[190:193], v[42:45]
	v_mfma_i32_16x16x64_i8 v[30:33], v[90:93], v[200:203], v[30:33]
	v_mfma_i32_16x16x64_i8 v[30:33], v[94:97], v[204:207], v[30:33]
	v_mfma_i32_16x16x64_i8 v[26:29], v[106:109], v[200:203], v[26:29]
	v_mfma_i32_16x16x64_i8 v[26:29], v[114:117], v[204:207], v[26:29]
	v_mfma_i32_16x16x64_i8 v[14:17], v[90:93], v[208:211], v[14:17]
	v_mfma_i32_16x16x64_i8 v[14:17], v[94:97], v[212:215], v[14:17]
	v_mfma_i32_16x16x64_i8 v[10:13], v[106:109], v[208:211], v[10:13]
	v_mfma_i32_16x16x64_i8 v[10:13], v[114:117], v[212:215], v[10:13]
	v_mfma_i32_16x16x64_i8 v[54:57], v[162:165], v[178:181], v[54:57]
	v_mfma_i32_16x16x64_i8 v[54:57], v[166:169], v[182:185], v[54:57]
	v_mfma_i32_16x16x64_i8 v[50:53], v[170:173], v[178:181], v[50:53]
	v_mfma_i32_16x16x64_i8 v[50:53], v[174:177], v[182:185], v[50:53]
	v_mfma_i32_16x16x64_i8 v[38:41], v[162:165], v[186:189], v[38:41]
	v_mfma_i32_16x16x64_i8 v[38:41], v[166:169], v[190:193], v[38:41]
	v_mfma_i32_16x16x64_i8 v[34:37], v[170:173], v[186:189], v[34:37]
	v_mfma_i32_16x16x64_i8 v[34:37], v[174:177], v[190:193], v[34:37]
	v_mfma_i32_16x16x64_i8 v[22:25], v[162:165], v[200:203], v[22:25]
	v_mfma_i32_16x16x64_i8 v[22:25], v[166:169], v[204:207], v[22:25]
	v_mfma_i32_16x16x64_i8 v[18:21], v[170:173], v[200:203], v[18:21]
	v_mfma_i32_16x16x64_i8 v[18:21], v[174:177], v[204:207], v[18:21]
	v_mfma_i32_16x16x64_i8 v[6:9], v[162:165], v[208:211], v[6:9]
	v_mfma_i32_16x16x64_i8 v[6:9], v[166:169], v[212:215], v[6:9]
	v_mfma_i32_16x16x64_i8 v[2:5], v[170:173], v[208:211], v[2:5]
	v_mfma_i32_16x16x64_i8 v[2:5], v[174:177], v[212:215], v[2:5]
	s_barrier
	s_add_i32 s66, 0, 0x18000
	s_add_i32 s67, 0, 0x1c000
	v_add_u32_e32 v114, s66, v157
	v_add_u32_e32 v156, s67, v157
	ds_read_b128 v[90:93], v114
	ds_read_b128 v[94:97], v114 offset:1024
	ds_read_b128 v[106:109], v114 offset:2048
	ds_read_b128 v[114:117], v114 offset:3072
	ds_read_b128 v[162:165], v156
	ds_read_b128 v[166:169], v156 offset:1024
	ds_read_b128 v[170:173], v156 offset:2048
	ds_read_b128 v[174:177], v156 offset:3072
	s_add_u32 s42, s42, 0x80000
	s_addc_u32 s43, s43, 0
	s_mov_b32 m0, s46
	v_lshl_add_u64 v[220:221], s[42:43], 0, v[150:151]
	ds_read_b128 v[178:181], v161 offset:32768
	ds_read_b128 v[182:185], v161 offset:33792
	ds_read_b128 v[186:189], v161 offset:34816
	ds_read_b128 v[190:193], v161 offset:35840
	ds_read_b128 v[200:203], v161 offset:36864
	ds_read_b128 v[204:207], v161 offset:37888
	ds_read_b128 v[208:211], v161 offset:38912
	ds_read_b128 v[212:215], v161 offset:39936
	global_load_lds_dwordx4 v[220:221], off
	v_lshl_add_u64 v[220:221], s[42:43], 0, v[148:149]
	s_mov_b32 m0, s47
	s_nop 0
	global_load_lds_dwordx4 v[220:221], off
	s_waitcnt vmcnt(8)
	s_waitcnt lgkmcnt(0)
	s_barrier
	s_waitcnt lgkmcnt(0)
	v_mfma_i32_16x16x64_i8 v[142:145], v[90:93], v[178:181], v[142:145]
	v_mfma_i32_16x16x64_i8 v[142:145], v[94:97], v[182:185], v[142:145]
	v_mfma_i32_16x16x64_i8 v[138:141], v[106:109], v[178:181], v[138:141]
	v_mfma_i32_16x16x64_i8 v[138:141], v[114:117], v[182:185], v[138:141]
	v_mfma_i32_16x16x64_i8 v[126:129], v[90:93], v[186:189], v[126:129]
	v_mfma_i32_16x16x64_i8 v[126:129], v[94:97], v[190:193], v[126:129]
	v_mfma_i32_16x16x64_i8 v[122:125], v[106:109], v[186:189], v[122:125]
	v_mfma_i32_16x16x64_i8 v[122:125], v[114:117], v[190:193], v[122:125]
	v_mfma_i32_16x16x64_i8 v[102:105], v[90:93], v[200:203], v[102:105]
	v_mfma_i32_16x16x64_i8 v[102:105], v[94:97], v[204:207], v[102:105]
	v_mfma_i32_16x16x64_i8 v[98:101], v[106:109], v[200:203], v[98:101]
	v_mfma_i32_16x16x64_i8 v[98:101], v[114:117], v[204:207], v[98:101]
	v_mfma_i32_16x16x64_i8 v[78:81], v[90:93], v[208:211], v[78:81]
	v_mfma_i32_16x16x64_i8 v[78:81], v[94:97], v[212:215], v[78:81]
	v_mfma_i32_16x16x64_i8 v[74:77], v[106:109], v[208:211], v[74:77]
	v_mfma_i32_16x16x64_i8 v[74:77], v[114:117], v[212:215], v[74:77]
	v_mfma_i32_16x16x64_i8 v[134:137], v[162:165], v[178:181], v[134:137]
	v_mfma_i32_16x16x64_i8 v[134:137], v[166:169], v[182:185], v[134:137]
	v_mfma_i32_16x16x64_i8 v[130:133], v[170:173], v[178:181], v[130:133]
	v_mfma_i32_16x16x64_i8 v[130:133], v[174:177], v[182:185], v[130:133]
	v_mfma_i32_16x16x64_i8 v[118:121], v[162:165], v[186:189], v[118:121]
	v_mfma_i32_16x16x64_i8 v[118:121], v[166:169], v[190:193], v[118:121]
	v_mfma_i32_16x16x64_i8 v[110:113], v[170:173], v[186:189], v[110:113]
	v_mfma_i32_16x16x64_i8 v[110:113], v[174:177], v[190:193], v[110:113]
	v_mfma_i32_16x16x64_i8 v[86:89], v[162:165], v[200:203], v[86:89]
	v_mfma_i32_16x16x64_i8 v[86:89], v[166:169], v[204:207], v[86:89]
	v_mfma_i32_16x16x64_i8 v[82:85], v[170:173], v[200:203], v[82:85]
	v_mfma_i32_16x16x64_i8 v[82:85], v[174:177], v[204:207], v[82:85]
	v_mfma_i32_16x16x64_i8 v[70:73], v[162:165], v[208:211], v[70:73]
	v_mfma_i32_16x16x64_i8 v[70:73], v[166:169], v[212:215], v[70:73]
	v_mfma_i32_16x16x64_i8 v[66:69], v[170:173], v[208:211], v[66:69]
	v_mfma_i32_16x16x64_i8 v[66:69], v[174:177], v[212:215], v[66:69]
	s_barrier
	s_add_i32 s42, s66, s9
	v_lshl_add_u64 v[158:159], v[158:159], 0, s[12:13]
	s_mov_b32 m0, s42
	ds_read_b128 v[178:181], v161 offset:49152
	ds_read_b128 v[182:185], v161 offset:50176
	ds_read_b128 v[186:189], v161 offset:51200
	ds_read_b128 v[190:193], v161 offset:52224
	ds_read_b128 v[200:203], v161 offset:53248
	ds_read_b128 v[204:207], v161 offset:54272
	ds_read_b128 v[208:211], v161 offset:55296
	ds_read_b128 v[212:215], v161 offset:56320
	global_load_lds_dwordx4 v[158:159], off
	s_add_i32 m0, s42, 0x2000
	s_add_u32 s34, s34, 0x80080
	v_lshl_add_u64 v[158:159], v[194:195], 0, s[12:13]
	s_addc_u32 s35, s35, 0
	s_add_i32 s42, s67, s9
	global_load_lds_dwordx4 v[158:159], off
	v_lshl_add_u64 v[158:159], s[34:35], 0, v[0:1]
	s_mov_b32 m0, s42
	s_nop 0
	global_load_lds_dwordx4 v[158:159], off
	v_lshl_add_u64 v[158:159], s[34:35], 0, v[146:147]
	s_add_i32 m0, s42, 0x2000
	s_nop 0
	global_load_lds_dwordx4 v[158:159], off
	v_lshl_add_u64 v[158:159], v[216:217], 0, s[12:13]
	s_mov_b32 m0, s50
	s_nop 0
	global_load_lds_dwordx4 v[158:159], off
	v_lshl_add_u64 v[158:159], v[218:219], 0, s[12:13]
	s_mov_b32 m0, s51
	s_nop 0
	global_load_lds_dwordx4 v[158:159], off
	s_waitcnt vmcnt(8)
	s_waitcnt lgkmcnt(0)
	s_barrier
	s_waitcnt lgkmcnt(0)
	v_mfma_i32_16x16x64_i8 v[62:65], v[90:93], v[178:181], v[62:65]
	v_mfma_i32_16x16x64_i8 v[62:65], v[94:97], v[182:185], v[62:65]
	v_mfma_i32_16x16x64_i8 v[58:61], v[106:109], v[178:181], v[58:61]
	v_mfma_i32_16x16x64_i8 v[58:61], v[114:117], v[182:185], v[58:61]
	v_mfma_i32_16x16x64_i8 v[46:49], v[90:93], v[186:189], v[46:49]
	v_mfma_i32_16x16x64_i8 v[46:49], v[94:97], v[190:193], v[46:49]
	v_mfma_i32_16x16x64_i8 v[42:45], v[106:109], v[186:189], v[42:45]
	v_mfma_i32_16x16x64_i8 v[42:45], v[114:117], v[190:193], v[42:45]
	v_mfma_i32_16x16x64_i8 v[30:33], v[90:93], v[200:203], v[30:33]
	v_mfma_i32_16x16x64_i8 v[30:33], v[94:97], v[204:207], v[30:33]
	v_mfma_i32_16x16x64_i8 v[26:29], v[106:109], v[200:203], v[26:29]
	v_mfma_i32_16x16x64_i8 v[26:29], v[114:117], v[204:207], v[26:29]
	v_mfma_i32_16x16x64_i8 v[14:17], v[90:93], v[208:211], v[14:17]
	v_mfma_i32_16x16x64_i8 v[14:17], v[94:97], v[212:215], v[14:17]
	v_mfma_i32_16x16x64_i8 v[10:13], v[106:109], v[208:211], v[10:13]
	v_mfma_i32_16x16x64_i8 v[10:13], v[114:117], v[212:215], v[10:13]
	v_mfma_i32_16x16x64_i8 v[54:57], v[162:165], v[178:181], v[54:57]
	v_mfma_i32_16x16x64_i8 v[54:57], v[166:169], v[182:185], v[54:57]
	v_mfma_i32_16x16x64_i8 v[50:53], v[170:173], v[178:181], v[50:53]
	v_mfma_i32_16x16x64_i8 v[50:53], v[174:177], v[182:185], v[50:53]
	v_mfma_i32_16x16x64_i8 v[38:41], v[162:165], v[186:189], v[38:41]
	v_mfma_i32_16x16x64_i8 v[38:41], v[166:169], v[190:193], v[38:41]
	v_mfma_i32_16x16x64_i8 v[34:37], v[170:173], v[186:189], v[34:37]
	v_mfma_i32_16x16x64_i8 v[34:37], v[174:177], v[190:193], v[34:37]
	v_mfma_i32_16x16x64_i8 v[22:25], v[162:165], v[200:203], v[22:25]
	v_mfma_i32_16x16x64_i8 v[22:25], v[166:169], v[204:207], v[22:25]
	v_mfma_i32_16x16x64_i8 v[18:21], v[170:173], v[200:203], v[18:21]
	v_mfma_i32_16x16x64_i8 v[18:21], v[174:177], v[204:207], v[18:21]
	v_mfma_i32_16x16x64_i8 v[6:9], v[162:165], v[208:211], v[6:9]
	v_mfma_i32_16x16x64_i8 v[6:9], v[166:169], v[212:215], v[6:9]
	v_mfma_i32_16x16x64_i8 v[2:5], v[170:173], v[208:211], v[2:5]
	v_mfma_i32_16x16x64_i8 v[2:5], v[174:177], v[212:215], v[2:5]
	s_barrier
	s_add_i32 s57, s57, 2
	s_add_u32 s30, s30, 0x100
	s_addc_u32 s31, s31, 0
	s_add_u32 s55, s55, 0x100
	s_addc_u32 s56, s56, 0
	s_cmp_gt_u32 s57, 29
	s_cbranch_scc0 .LBB0_779
	s_and_b64 vcc, exec, s[20:21]
	s_mov_b32 s54, 0x5c401000
	s_cbranch_vccz .LBB0_782
	s_barrier

.LBB0_801:
	s_add_u32 s34, s30, 0xfff00080
	s_addc_u32 s35, s31, -1
	s_add_i32 s54, 0, 0x10000
	s_cmp_eq_u32 s53, 60
	s_cselect_b32 s41, s25, s35
	s_cselect_b32 s40, s49, s34
	s_cselect_b32 s35, s23, s52
	s_cselect_b32 s34, s50, s51
	s_add_i32 s56, 0, 0x14000
	v_add_u32_e32 v156, s54, v141
	v_add_u32_e32 v172, s56, v141
	ds_read_b128 v[144:147], v156
	ds_read_b128 v[148:151], v156 offset:1024
	ds_read_b128 v[152:155], v156 offset:2048
	ds_read_b128 v[156:159], v156 offset:3072
	ds_read_b128 v[160:163], v172
	ds_read_b128 v[164:167], v172 offset:1024
	ds_read_b128 v[168:171], v172 offset:2048
	ds_read_b128 v[172:175], v172 offset:3072
	v_lshl_add_u64 v[212:213], s[30:31], 0, v[136:137]
	s_add_i32 m0, s14, 0xc000
	ds_read_b128 v[176:179], v143
	ds_read_b128 v[180:183], v143 offset:1024
	ds_read_b128 v[184:187], v143 offset:2048
	ds_read_b128 v[188:191], v143 offset:3072
	ds_read_b128 v[192:195], v143 offset:4096
	ds_read_b128 v[200:203], v143 offset:5120
	ds_read_b128 v[204:207], v143 offset:6144
	ds_read_b128 v[208:211], v143 offset:7168
	global_load_lds_dwordx4 v[212:213], off
	v_lshl_add_u64 v[212:213], s[30:31], 0, v[138:139]
	s_add_i32 m0, s14, 0xe000
	s_nop 0
	global_load_lds_dwordx4 v[212:213], off
	s_waitcnt vmcnt(8)
	s_waitcnt lgkmcnt(0)
	s_barrier
	s_waitcnt lgkmcnt(0)
	v_mfma_f32_16x16x32_bf16 v[126:129], v[144:147], v[176:179], v[126:129]
	v_mfma_f32_16x16x32_bf16 v[126:129], v[148:151], v[180:183], v[126:129]
	v_mfma_f32_16x16x32_bf16 v[122:125], v[152:155], v[176:179], v[122:125]
	v_mfma_f32_16x16x32_bf16 v[122:125], v[156:159], v[180:183], v[122:125]
	v_mfma_f32_16x16x32_bf16 v[118:121], v[144:147], v[184:187], v[118:121]
	v_mfma_f32_16x16x32_bf16 v[118:121], v[148:151], v[188:191], v[118:121]
	v_mfma_f32_16x16x32_bf16 v[114:117], v[152:155], v[184:187], v[114:117]
	v_mfma_f32_16x16x32_bf16 v[114:117], v[156:159], v[188:191], v[114:117]
	v_mfma_f32_16x16x32_bf16 v[102:105], v[144:147], v[192:195], v[102:105]
	v_mfma_f32_16x16x32_bf16 v[102:105], v[148:151], v[200:203], v[102:105]
	v_mfma_f32_16x16x32_bf16 v[98:101], v[152:155], v[192:195], v[98:101]
	v_mfma_f32_16x16x32_bf16 v[98:101], v[156:159], v[200:203], v[98:101]
	v_mfma_f32_16x16x32_bf16 v[86:89], v[144:147], v[204:207], v[86:89]
	v_mfma_f32_16x16x32_bf16 v[86:89], v[148:151], v[208:211], v[86:89]
	v_mfma_f32_16x16x32_bf16 v[82:85], v[152:155], v[204:207], v[82:85]
	v_mfma_f32_16x16x32_bf16 v[82:85], v[156:159], v[208:211], v[82:85]
	v_mfma_f32_16x16x32_bf16 v[110:113], v[160:163], v[176:179], v[110:113]
	v_mfma_f32_16x16x32_bf16 v[110:113], v[164:167], v[180:183], v[110:113]
	v_mfma_f32_16x16x32_bf16 v[106:109], v[168:171], v[176:179], v[106:109]
	v_mfma_f32_16x16x32_bf16 v[106:109], v[172:175], v[180:183], v[106:109]
	v_mfma_f32_16x16x32_bf16 v[94:97], v[160:163], v[184:187], v[94:97]
	v_mfma_f32_16x16x32_bf16 v[94:97], v[164:167], v[188:191], v[94:97]
	v_mfma_f32_16x16x32_bf16 v[90:93], v[168:171], v[184:187], v[90:93]
	v_mfma_f32_16x16x32_bf16 v[90:93], v[172:175], v[188:191], v[90:93]
	v_mfma_f32_16x16x32_bf16 v[78:81], v[160:163], v[192:195], v[78:81]
	v_mfma_f32_16x16x32_bf16 v[78:81], v[164:167], v[200:203], v[78:81]
	v_mfma_f32_16x16x32_bf16 v[74:77], v[168:171], v[192:195], v[74:77]
	v_mfma_f32_16x16x32_bf16 v[74:77], v[172:175], v[200:203], v[74:77]
	v_mfma_f32_16x16x32_bf16 v[70:73], v[160:163], v[204:207], v[70:73]
	v_mfma_f32_16x16x32_bf16 v[70:73], v[164:167], v[208:211], v[70:73]
	v_mfma_f32_16x16x32_bf16 v[66:69], v[168:171], v[204:207], v[66:69]
	v_mfma_f32_16x16x32_bf16 v[66:69], v[172:175], v[208:211], v[66:69]
	s_barrier
	s_add_i32 s54, s54, s9
	v_lshl_add_u64 v[212:213], s[34:35], 0, v[0:1]
	s_mov_b32 m0, s54
	ds_read_b128 v[176:179], v143 offset:16384
	ds_read_b128 v[180:183], v143 offset:17408
	ds_read_b128 v[184:187], v143 offset:18432
	ds_read_b128 v[188:191], v143 offset:19456
	ds_read_b128 v[192:195], v143 offset:20480
	ds_read_b128 v[200:203], v143 offset:21504
	ds_read_b128 v[204:207], v143 offset:22528
	ds_read_b128 v[208:211], v143 offset:23552
	global_load_lds_dwordx4 v[212:213], off
	s_add_i32 m0, s54, 0x2000
	s_add_u32 s54, s34, 0x100000
	v_lshl_add_u64 v[214:215], s[34:35], 0, v[130:131]
	s_addc_u32 s55, s35, 0
	s_add_i32 s56, s56, s9
	global_load_lds_dwordx4 v[214:215], off
	v_lshl_add_u64 v[216:217], s[54:55], 0, v[0:1]
	s_mov_b32 m0, s56
	v_lshl_add_u64 v[218:219], s[40:41], 0, v[132:133]
	global_load_lds_dwordx4 v[216:217], off
	v_lshl_add_u64 v[216:217], s[54:55], 0, v[130:131]
	s_add_i32 m0, s56, 0x2000
	s_nop 0
	global_load_lds_dwordx4 v[216:217], off
	v_lshl_add_u64 v[216:217], s[40:41], 0, v[134:135]
	s_mov_b32 m0, s14
	s_nop 0
	global_load_lds_dwordx4 v[216:217], off
	s_mov_b32 m0, s15
	s_nop 0
	global_load_lds_dwordx4 v[218:219], off
	s_waitcnt vmcnt(8)
	s_waitcnt lgkmcnt(0)
	s_barrier
	s_waitcnt lgkmcnt(0)
	v_mfma_f32_16x16x32_bf16 v[62:65], v[144:147], v[176:179], v[62:65]
	v_mfma_f32_16x16x32_bf16 v[62:65], v[148:151], v[180:183], v[62:65]
	v_mfma_f32_16x16x32_bf16 v[58:61], v[152:155], v[176:179], v[58:61]
	v_mfma_f32_16x16x32_bf16 v[58:61], v[156:159], v[180:183], v[58:61]
	v_mfma_f32_16x16x32_bf16 v[54:57], v[144:147], v[184:187], v[54:57]
	v_mfma_f32_16x16x32_bf16 v[54:57], v[148:151], v[188:191], v[54:57]
	v_mfma_f32_16x16x32_bf16 v[50:53], v[152:155], v[184:187], v[50:53]
	v_mfma_f32_16x16x32_bf16 v[50:53], v[156:159], v[188:191], v[50:53]
	v_mfma_f32_16x16x32_bf16 v[38:41], v[144:147], v[192:195], v[38:41]
	v_mfma_f32_16x16x32_bf16 v[38:41], v[148:151], v[200:203], v[38:41]
	v_mfma_f32_16x16x32_bf16 v[34:37], v[152:155], v[192:195], v[34:37]
	v_mfma_f32_16x16x32_bf16 v[34:37], v[156:159], v[200:203], v[34:37]
	v_mfma_f32_16x16x32_bf16 v[22:25], v[144:147], v[204:207], v[22:25]
	v_mfma_f32_16x16x32_bf16 v[22:25], v[148:151], v[208:211], v[22:25]
	v_mfma_f32_16x16x32_bf16 v[18:21], v[152:155], v[204:207], v[18:21]
	v_mfma_f32_16x16x32_bf16 v[18:21], v[156:159], v[208:211], v[18:21]
	v_mfma_f32_16x16x32_bf16 v[46:49], v[160:163], v[176:179], v[46:49]
	v_mfma_f32_16x16x32_bf16 v[46:49], v[164:167], v[180:183], v[46:49]
	v_mfma_f32_16x16x32_bf16 v[42:45], v[168:171], v[176:179], v[42:45]
	v_mfma_f32_16x16x32_bf16 v[42:45], v[172:175], v[180:183], v[42:45]
	v_mfma_f32_16x16x32_bf16 v[30:33], v[160:163], v[184:187], v[30:33]
	v_mfma_f32_16x16x32_bf16 v[30:33], v[164:167], v[188:191], v[30:33]
	v_mfma_f32_16x16x32_bf16 v[26:29], v[168:171], v[184:187], v[26:29]
	v_mfma_f32_16x16x32_bf16 v[26:29], v[172:175], v[188:191], v[26:29]
	v_mfma_f32_16x16x32_bf16 v[14:17], v[160:163], v[192:195], v[14:17]
	v_mfma_f32_16x16x32_bf16 v[14:17], v[164:167], v[200:203], v[14:17]
	v_mfma_f32_16x16x32_bf16 v[10:13], v[168:171], v[192:195], v[10:13]
	v_mfma_f32_16x16x32_bf16 v[10:13], v[172:175], v[200:203], v[10:13]
	v_mfma_f32_16x16x32_bf16 v[6:9], v[160:163], v[204:207], v[6:9]
	v_mfma_f32_16x16x32_bf16 v[6:9], v[164:167], v[208:211], v[6:9]
	v_mfma_f32_16x16x32_bf16 v[2:5], v[168:171], v[204:207], v[2:5]
	v_mfma_f32_16x16x32_bf16 v[2:5], v[172:175], v[208:211], v[2:5]
	s_barrier
	s_add_i32 s54, 0, 0x18000
	s_add_i32 s55, 0, 0x1c000
	v_add_u32_e32 v156, s54, v141
	v_add_u32_e32 v172, s55, v141
	ds_read_b128 v[144:147], v156
	ds_read_b128 v[148:151], v156 offset:1024
	ds_read_b128 v[152:155], v156 offset:2048
	ds_read_b128 v[156:159], v156 offset:3072
	ds_read_b128 v[160:163], v172
	ds_read_b128 v[164:167], v172 offset:1024
	ds_read_b128 v[168:171], v172 offset:2048
	ds_read_b128 v[172:175], v172 offset:3072
	s_add_u32 s40, s40, 0x100000
	s_addc_u32 s41, s41, 0
	s_mov_b32 m0, s18
	v_lshl_add_u64 v[220:221], s[40:41], 0, v[134:135]
	ds_read_b128 v[176:179], v143 offset:32768
	ds_read_b128 v[180:183], v143 offset:33792
	ds_read_b128 v[184:187], v143 offset:34816
	ds_read_b128 v[188:191], v143 offset:35840
	ds_read_b128 v[192:195], v143 offset:36864
	ds_read_b128 v[200:203], v143 offset:37888
	ds_read_b128 v[204:207], v143 offset:38912
	ds_read_b128 v[208:211], v143 offset:39936
	global_load_lds_dwordx4 v[220:221], off
	v_lshl_add_u64 v[220:221], s[40:41], 0, v[132:133]
	s_mov_b32 m0, s19
	s_nop 0
	global_load_lds_dwordx4 v[220:221], off
	s_waitcnt vmcnt(8)
	s_waitcnt lgkmcnt(0)
	s_barrier
	s_waitcnt lgkmcnt(0)
	v_mfma_f32_16x16x32_bf16 v[126:129], v[144:147], v[176:179], v[126:129]
	v_mfma_f32_16x16x32_bf16 v[126:129], v[148:151], v[180:183], v[126:129]
	v_mfma_f32_16x16x32_bf16 v[122:125], v[152:155], v[176:179], v[122:125]
	v_mfma_f32_16x16x32_bf16 v[122:125], v[156:159], v[180:183], v[122:125]
	v_mfma_f32_16x16x32_bf16 v[118:121], v[144:147], v[184:187], v[118:121]
	v_mfma_f32_16x16x32_bf16 v[118:121], v[148:151], v[188:191], v[118:121]
	v_mfma_f32_16x16x32_bf16 v[114:117], v[152:155], v[184:187], v[114:117]
	v_mfma_f32_16x16x32_bf16 v[114:117], v[156:159], v[188:191], v[114:117]
	v_mfma_f32_16x16x32_bf16 v[102:105], v[144:147], v[192:195], v[102:105]
	v_mfma_f32_16x16x32_bf16 v[102:105], v[148:151], v[200:203], v[102:105]
	v_mfma_f32_16x16x32_bf16 v[98:101], v[152:155], v[192:195], v[98:101]
	v_mfma_f32_16x16x32_bf16 v[98:101], v[156:159], v[200:203], v[98:101]
	v_mfma_f32_16x16x32_bf16 v[86:89], v[144:147], v[204:207], v[86:89]
	v_mfma_f32_16x16x32_bf16 v[86:89], v[148:151], v[208:211], v[86:89]
	v_mfma_f32_16x16x32_bf16 v[82:85], v[152:155], v[204:207], v[82:85]
	v_mfma_f32_16x16x32_bf16 v[82:85], v[156:159], v[208:211], v[82:85]
	v_mfma_f32_16x16x32_bf16 v[110:113], v[160:163], v[176:179], v[110:113]
	v_mfma_f32_16x16x32_bf16 v[110:113], v[164:167], v[180:183], v[110:113]
	v_mfma_f32_16x16x32_bf16 v[106:109], v[168:171], v[176:179], v[106:109]
	v_mfma_f32_16x16x32_bf16 v[106:109], v[172:175], v[180:183], v[106:109]
	v_mfma_f32_16x16x32_bf16 v[94:97], v[160:163], v[184:187], v[94:97]
	v_mfma_f32_16x16x32_bf16 v[94:97], v[164:167], v[188:191], v[94:97]
	v_mfma_f32_16x16x32_bf16 v[90:93], v[168:171], v[184:187], v[90:93]
	v_mfma_f32_16x16x32_bf16 v[90:93], v[172:175], v[188:191], v[90:93]
	v_mfma_f32_16x16x32_bf16 v[78:81], v[160:163], v[192:195], v[78:81]
	v_mfma_f32_16x16x32_bf16 v[78:81], v[164:167], v[200:203], v[78:81]
	v_mfma_f32_16x16x32_bf16 v[74:77], v[168:171], v[192:195], v[74:77]
	v_mfma_f32_16x16x32_bf16 v[74:77], v[172:175], v[200:203], v[74:77]
	v_mfma_f32_16x16x32_bf16 v[70:73], v[160:163], v[204:207], v[70:73]
	v_mfma_f32_16x16x32_bf16 v[70:73], v[164:167], v[208:211], v[70:73]
	v_mfma_f32_16x16x32_bf16 v[66:69], v[168:171], v[204:207], v[66:69]
	v_mfma_f32_16x16x32_bf16 v[66:69], v[172:175], v[208:211], v[66:69]
	s_barrier
	s_add_i32 s40, s54, s9
	v_lshl_add_u64 v[212:213], v[212:213], 0, s[12:13]
	s_mov_b32 m0, s40
	ds_read_b128 v[176:179], v143 offset:49152
	ds_read_b128 v[180:183], v143 offset:50176
	ds_read_b128 v[184:187], v143 offset:51200
	ds_read_b128 v[188:191], v143 offset:52224
	ds_read_b128 v[192:195], v143 offset:53248
	ds_read_b128 v[200:203], v143 offset:54272
	ds_read_b128 v[204:207], v143 offset:55296
	ds_read_b128 v[208:211], v143 offset:56320
	global_load_lds_dwordx4 v[212:213], off
	s_add_i32 m0, s40, 0x2000
	s_add_u32 s34, s34, 0x100080
	v_lshl_add_u64 v[212:213], v[214:215], 0, s[12:13]
	s_addc_u32 s35, s35, 0
	s_add_i32 s40, s55, s9
	global_load_lds_dwordx4 v[212:213], off
	v_lshl_add_u64 v[212:213], s[34:35], 0, v[0:1]
	s_mov_b32 m0, s40
	s_nop 0
	global_load_lds_dwordx4 v[212:213], off
	v_lshl_add_u64 v[212:213], s[34:35], 0, v[130:131]
	s_add_i32 m0, s40, 0x2000
	s_nop 0
	global_load_lds_dwordx4 v[212:213], off
	v_lshl_add_u64 v[212:213], v[216:217], 0, s[12:13]
	s_mov_b32 m0, s42
	s_nop 0
	global_load_lds_dwordx4 v[212:213], off
	v_lshl_add_u64 v[212:213], v[218:219], 0, s[12:13]
	s_mov_b32 m0, s43
	s_nop 0
	global_load_lds_dwordx4 v[212:213], off
	s_waitcnt vmcnt(8)
	s_waitcnt lgkmcnt(0)
	s_barrier
	s_waitcnt lgkmcnt(0)
	v_mfma_f32_16x16x32_bf16 v[62:65], v[144:147], v[176:179], v[62:65]
	v_mfma_f32_16x16x32_bf16 v[62:65], v[148:151], v[180:183], v[62:65]
	v_mfma_f32_16x16x32_bf16 v[58:61], v[152:155], v[176:179], v[58:61]
	v_mfma_f32_16x16x32_bf16 v[58:61], v[156:159], v[180:183], v[58:61]
	v_mfma_f32_16x16x32_bf16 v[54:57], v[144:147], v[184:187], v[54:57]
	v_mfma_f32_16x16x32_bf16 v[54:57], v[148:151], v[188:191], v[54:57]
	v_mfma_f32_16x16x32_bf16 v[50:53], v[152:155], v[184:187], v[50:53]
	v_mfma_f32_16x16x32_bf16 v[50:53], v[156:159], v[188:191], v[50:53]
	v_mfma_f32_16x16x32_bf16 v[38:41], v[144:147], v[192:195], v[38:41]
	v_mfma_f32_16x16x32_bf16 v[38:41], v[148:151], v[200:203], v[38:41]
	v_mfma_f32_16x16x32_bf16 v[34:37], v[152:155], v[192:195], v[34:37]
	v_mfma_f32_16x16x32_bf16 v[34:37], v[156:159], v[200:203], v[34:37]
	v_mfma_f32_16x16x32_bf16 v[22:25], v[144:147], v[204:207], v[22:25]
	v_mfma_f32_16x16x32_bf16 v[22:25], v[148:151], v[208:211], v[22:25]
	v_mfma_f32_16x16x32_bf16 v[18:21], v[152:155], v[204:207], v[18:21]
	v_mfma_f32_16x16x32_bf16 v[18:21], v[156:159], v[208:211], v[18:21]
	v_mfma_f32_16x16x32_bf16 v[46:49], v[160:163], v[176:179], v[46:49]
	v_mfma_f32_16x16x32_bf16 v[46:49], v[164:167], v[180:183], v[46:49]
	v_mfma_f32_16x16x32_bf16 v[42:45], v[168:171], v[176:179], v[42:45]
	v_mfma_f32_16x16x32_bf16 v[42:45], v[172:175], v[180:183], v[42:45]
	v_mfma_f32_16x16x32_bf16 v[30:33], v[160:163], v[184:187], v[30:33]
	v_mfma_f32_16x16x32_bf16 v[30:33], v[164:167], v[188:191], v[30:33]
	v_mfma_f32_16x16x32_bf16 v[26:29], v[168:171], v[184:187], v[26:29]
	v_mfma_f32_16x16x32_bf16 v[26:29], v[172:175], v[188:191], v[26:29]
	v_mfma_f32_16x16x32_bf16 v[14:17], v[160:163], v[192:195], v[14:17]
	v_mfma_f32_16x16x32_bf16 v[14:17], v[164:167], v[200:203], v[14:17]
	v_mfma_f32_16x16x32_bf16 v[10:13], v[168:171], v[192:195], v[10:13]
	v_mfma_f32_16x16x32_bf16 v[10:13], v[172:175], v[200:203], v[10:13]
	v_mfma_f32_16x16x32_bf16 v[6:9], v[160:163], v[204:207], v[6:9]
	v_mfma_f32_16x16x32_bf16 v[6:9], v[164:167], v[208:211], v[6:9]
	v_mfma_f32_16x16x32_bf16 v[2:5], v[168:171], v[204:207], v[2:5]
	v_mfma_f32_16x16x32_bf16 v[2:5], v[172:175], v[208:211], v[2:5]
	s_barrier
	s_add_i32 s53, s53, 2
	s_add_u32 s30, s30, 0x100
	s_addc_u32 s31, s31, 0
	s_add_u32 s51, s51, 0x100
	s_addc_u32 s52, s52, 0
	s_cmp_gt_u32 s53, 61
	s_cbranch_scc0 .LBB0_801
	s_and_b64 vcc, exec, s[20:21]
	s_cbranch_vccz .LBB0_804
	s_barrier
